# one static s_setprio 1 for waves 4-7 around every GEMM K-loop (reset to 0 after the loop), on top of the attention PV pipelining
# baseline (speedup 1.0000x reference)
.LBB0_215:
	s_ashr_i32 s13, s12, 31
	s_lshl_b64 s[16:17], s[12:13], 21
	s_add_u32 s16, s70, s16
	s_addc_u32 s17, s71, s17
	s_and_b64 s[18:19], s[2:3], exec
	s_cselect_b32 s13, s17, s1
	s_cselect_b32 s24, s16, s0
	s_ashr_i32 s15, s14, 31
	s_lshl_b64 s[18:19], s[14:15], 21
	s_add_u32 s18, s6, s18
	s_addc_u32 s19, s7, s19
	s_and_b64 s[22:23], s[2:3], exec
	s_cselect_b32 s15, s19, s21
	s_cselect_b32 s25, s18, s20
	s_add_u32 s0, s0, 0x100080
	s_addc_u32 s1, s1, 0
	s_add_u32 s27, s20, 0x100
	v_mov_b32_e32 v2, 0
	s_addc_u32 s29, s21, 0
	s_mov_b32 s30, -2
	v_mov_b64_e32 v[2:3], 0
	v_mov_b64_e32 v[4:5], 0
	v_mov_b64_e32 v[6:7], 0
	v_mov_b64_e32 v[8:9], 0
	v_mov_b64_e32 v[10:11], 0
	v_mov_b64_e32 v[12:13], 0
	v_mov_b64_e32 v[14:15], 0
	v_mov_b64_e32 v[16:17], 0
	v_mov_b64_e32 v[18:19], 0
	v_mov_b64_e32 v[20:21], 0
	v_mov_b64_e32 v[22:23], 0
	v_mov_b64_e32 v[24:25], 0
	v_mov_b64_e32 v[26:27], 0
	v_mov_b64_e32 v[28:29], 0
	v_mov_b64_e32 v[30:31], 0
	v_mov_b64_e32 v[32:33], 0
	v_mov_b64_e32 v[34:35], 0
	v_mov_b64_e32 v[36:37], 0
	v_mov_b64_e32 v[38:39], 0
	v_mov_b64_e32 v[40:41], 0
	v_mov_b64_e32 v[42:43], 0
	v_mov_b64_e32 v[44:45], 0
	v_mov_b64_e32 v[46:47], 0
	v_mov_b64_e32 v[48:49], 0
	v_mov_b64_e32 v[50:51], 0
	v_mov_b64_e32 v[52:53], 0
	v_mov_b64_e32 v[54:55], 0
	v_mov_b64_e32 v[56:57], 0
	v_mov_b64_e32 v[58:59], 0
	v_mov_b64_e32 v[60:61], 0
	v_mov_b64_e32 v[62:63], 0
	v_mov_b64_e32 v[64:65], 0
	v_mov_b64_e32 v[66:67], 0
	v_mov_b64_e32 v[68:69], 0
	v_mov_b64_e32 v[70:71], 0
	v_mov_b64_e32 v[72:73], 0
	v_mov_b64_e32 v[74:75], 0
	v_mov_b64_e32 v[76:77], 0
	v_mov_b64_e32 v[78:79], 0
	v_mov_b64_e32 v[80:81], 0
	v_mov_b64_e32 v[82:83], 0
	v_mov_b64_e32 v[84:85], 0
	v_mov_b64_e32 v[86:87], 0
	v_mov_b64_e32 v[88:89], 0
	v_mov_b64_e32 v[90:91], 0
	v_mov_b64_e32 v[92:93], 0
	v_mov_b64_e32 v[94:95], 0
	v_mov_b64_e32 v[96:97], 0
	v_mov_b64_e32 v[98:99], 0
	v_mov_b64_e32 v[100:101], 0
	v_mov_b64_e32 v[102:103], 0
	v_mov_b64_e32 v[104:105], 0
	v_mov_b64_e32 v[106:107], 0
	v_mov_b64_e32 v[108:109], 0
	v_mov_b64_e32 v[110:111], 0
	v_mov_b64_e32 v[112:113], 0
	v_mov_b64_e32 v[114:115], 0
	v_mov_b64_e32 v[116:117], 0
	v_mov_b64_e32 v[118:119], 0
	v_mov_b64_e32 v[120:121], 0
	v_mov_b64_e32 v[122:123], 0
	v_mov_b64_e32 v[124:125], 0
	v_mov_b64_e32 v[126:127], 0
	v_mov_b64_e32 v[128:129], 0
	v_add_u32_e32 v246, 0x18000, v158
	v_add_u32_e32 v247, 0x1c000, v158
	v_cmp_gt_u32_e32 vcc, 0x100, v0
	s_cbranch_vccnz .Lgprio_216
	s_setprio 1
.Lgprio_216:
.LBB0_216:
	ds_read_b128 v[152:155], v160
	ds_read_b128 v[164:167], v160 offset:1024
	ds_read_b128 v[168:171], v160 offset:2048
	ds_read_b128 v[172:175], v160 offset:3072
	ds_read_b128 v[176:179], v161
	ds_read_b128 v[180:183], v161 offset:1024
	ds_read_b128 v[184:187], v161 offset:2048
	ds_read_b128 v[188:191], v161 offset:3072
	s_add_u32 s20, s0, 0xfff00080
	s_addc_u32 s21, s1, -1
	s_cmp_eq_u32 s30, 60
	s_cselect_b32 s23, s13, s21
	s_cselect_b32 s22, s24, s20
	s_cselect_b32 s21, s15, s29
	s_cselect_b32 s20, s25, s27
	s_add_i32 m0, s39, 0xc000
	ds_read_b128 v[192:195], v162
	ds_read_b128 v[196:199], v162 offset:1024
	ds_read_b128 v[200:203], v162 offset:2048
	ds_read_b128 v[204:207], v162 offset:3072
	ds_read_b128 v[208:211], v162 offset:4096
	ds_read_b128 v[212:215], v162 offset:5120
	ds_read_b128 v[216:219], v162 offset:6144
	ds_read_b128 v[220:223], v162 offset:7168
	global_load_lds_dwordx4 v140, s[0:1]
	s_add_i32 m0, s39, 0xe000
	s_nop 0
	global_load_lds_dwordx4 v142, s[0:1]
	s_waitcnt vmcnt(8)
	s_waitcnt lgkmcnt(0)
	s_barrier
	v_mfma_f32_16x16x32_bf16 v[126:129], v[152:155], v[192:195], v[126:129]
	v_mfma_f32_16x16x32_bf16 v[126:129], v[164:167], v[196:199], v[126:129]
	v_mfma_f32_16x16x32_bf16 v[122:125], v[168:171], v[192:195], v[122:125]
	v_mfma_f32_16x16x32_bf16 v[122:125], v[172:175], v[196:199], v[122:125]
	v_mfma_f32_16x16x32_bf16 v[114:117], v[152:155], v[200:203], v[114:117]
	v_mfma_f32_16x16x32_bf16 v[114:117], v[164:167], v[204:207], v[114:117]
	v_mfma_f32_16x16x32_bf16 v[106:109], v[168:171], v[200:203], v[106:109]
	v_mfma_f32_16x16x32_bf16 v[106:109], v[172:175], v[204:207], v[106:109]
	v_mfma_f32_16x16x32_bf16 v[98:101], v[152:155], v[208:211], v[98:101]
	v_mfma_f32_16x16x32_bf16 v[98:101], v[164:167], v[212:215], v[98:101]
	v_mfma_f32_16x16x32_bf16 v[90:93], v[168:171], v[208:211], v[90:93]
	v_mfma_f32_16x16x32_bf16 v[90:93], v[172:175], v[212:215], v[90:93]
	v_mfma_f32_16x16x32_bf16 v[82:85], v[152:155], v[216:219], v[82:85]
	v_mfma_f32_16x16x32_bf16 v[82:85], v[164:167], v[220:223], v[82:85]
	v_mfma_f32_16x16x32_bf16 v[74:77], v[168:171], v[216:219], v[74:77]
	v_mfma_f32_16x16x32_bf16 v[74:77], v[172:175], v[220:223], v[74:77]
	v_mfma_f32_16x16x32_bf16 v[118:121], v[176:179], v[192:195], v[118:121]
	v_mfma_f32_16x16x32_bf16 v[118:121], v[180:183], v[196:199], v[118:121]
	v_mfma_f32_16x16x32_bf16 v[110:113], v[184:187], v[192:195], v[110:113]
	v_mfma_f32_16x16x32_bf16 v[110:113], v[188:191], v[196:199], v[110:113]
	v_mfma_f32_16x16x32_bf16 v[102:105], v[176:179], v[200:203], v[102:105]
	v_mfma_f32_16x16x32_bf16 v[102:105], v[180:183], v[204:207], v[102:105]
	v_mfma_f32_16x16x32_bf16 v[94:97], v[184:187], v[200:203], v[94:97]
	v_mfma_f32_16x16x32_bf16 v[94:97], v[188:191], v[204:207], v[94:97]
	v_mfma_f32_16x16x32_bf16 v[86:89], v[176:179], v[208:211], v[86:89]
	v_mfma_f32_16x16x32_bf16 v[86:89], v[180:183], v[212:215], v[86:89]
	v_mfma_f32_16x16x32_bf16 v[78:81], v[184:187], v[208:211], v[78:81]
	v_mfma_f32_16x16x32_bf16 v[78:81], v[188:191], v[212:215], v[78:81]
	v_mfma_f32_16x16x32_bf16 v[70:73], v[176:179], v[216:219], v[70:73]
	v_mfma_f32_16x16x32_bf16 v[70:73], v[180:183], v[220:223], v[70:73]
	v_mfma_f32_16x16x32_bf16 v[66:69], v[184:187], v[216:219], v[66:69]
	v_mfma_f32_16x16x32_bf16 v[66:69], v[188:191], v[220:223], v[66:69]
	s_barrier
	s_add_i32 s31, s49, s38
	s_mov_b32 m0, s31
	ds_read_b128 v[192:195], v162 offset:16384
	ds_read_b128 v[196:199], v162 offset:17408
	ds_read_b128 v[200:203], v162 offset:18432
	ds_read_b128 v[204:207], v162 offset:19456
	ds_read_b128 v[208:211], v162 offset:20480
	ds_read_b128 v[212:215], v162 offset:21504
	ds_read_b128 v[216:219], v162 offset:22528
	ds_read_b128 v[220:223], v162 offset:23552
	global_load_lds_dwordx4 v132, s[20:21]
	s_add_i32 m0, s31, 0x2000
	s_add_u32 s34, s20, 0x100000
	s_addc_u32 s35, s21, 0
	s_add_i32 s31, s50, s38
	global_load_lds_dwordx4 v136, s[20:21]
	s_mov_b32 m0, s31
	global_load_lds_dwordx4 v132, s[34:35]
	s_add_i32 m0, s31, 0x2000
	s_nop 0
	global_load_lds_dwordx4 v136, s[34:35]
	s_mov_b32 m0, s39
	s_nop 0
	global_load_lds_dwordx4 v130, s[22:23]
	s_mov_b32 m0, s40
	s_nop 0
	global_load_lds_dwordx4 v134, s[22:23]
	s_waitcnt vmcnt(8)
	s_waitcnt lgkmcnt(0)
	s_barrier
	v_mfma_f32_16x16x32_bf16 v[62:65], v[152:155], v[192:195], v[62:65]
	v_mfma_f32_16x16x32_bf16 v[62:65], v[164:167], v[196:199], v[62:65]
	v_mfma_f32_16x16x32_bf16 v[58:61], v[168:171], v[192:195], v[58:61]
	v_mfma_f32_16x16x32_bf16 v[58:61], v[172:175], v[196:199], v[58:61]
	v_mfma_f32_16x16x32_bf16 v[46:49], v[152:155], v[200:203], v[46:49]
	v_mfma_f32_16x16x32_bf16 v[46:49], v[164:167], v[204:207], v[46:49]
	v_mfma_f32_16x16x32_bf16 v[42:45], v[168:171], v[200:203], v[42:45]
	v_mfma_f32_16x16x32_bf16 v[42:45], v[172:175], v[204:207], v[42:45]
	v_mfma_f32_16x16x32_bf16 v[30:33], v[152:155], v[208:211], v[30:33]
	v_mfma_f32_16x16x32_bf16 v[30:33], v[164:167], v[212:215], v[30:33]
	v_mfma_f32_16x16x32_bf16 v[26:29], v[168:171], v[208:211], v[26:29]
	v_mfma_f32_16x16x32_bf16 v[26:29], v[172:175], v[212:215], v[26:29]
	v_mfma_f32_16x16x32_bf16 v[14:17], v[152:155], v[216:219], v[14:17]
	v_mfma_f32_16x16x32_bf16 v[14:17], v[164:167], v[220:223], v[14:17]
	v_mfma_f32_16x16x32_bf16 v[10:13], v[168:171], v[216:219], v[10:13]
	v_mfma_f32_16x16x32_bf16 v[10:13], v[172:175], v[220:223], v[10:13]
	v_mfma_f32_16x16x32_bf16 v[54:57], v[176:179], v[192:195], v[54:57]
	v_mfma_f32_16x16x32_bf16 v[54:57], v[180:183], v[196:199], v[54:57]
	v_mfma_f32_16x16x32_bf16 v[50:53], v[184:187], v[192:195], v[50:53]
	v_mfma_f32_16x16x32_bf16 v[50:53], v[188:191], v[196:199], v[50:53]
	v_mfma_f32_16x16x32_bf16 v[38:41], v[176:179], v[200:203], v[38:41]
	v_mfma_f32_16x16x32_bf16 v[38:41], v[180:183], v[204:207], v[38:41]
	v_mfma_f32_16x16x32_bf16 v[34:37], v[184:187], v[200:203], v[34:37]
	v_mfma_f32_16x16x32_bf16 v[34:37], v[188:191], v[204:207], v[34:37]
	v_mfma_f32_16x16x32_bf16 v[22:25], v[176:179], v[208:211], v[22:25]
	v_mfma_f32_16x16x32_bf16 v[22:25], v[180:183], v[212:215], v[22:25]
	v_mfma_f32_16x16x32_bf16 v[18:21], v[184:187], v[208:211], v[18:21]
	v_mfma_f32_16x16x32_bf16 v[18:21], v[188:191], v[212:215], v[18:21]
	v_mfma_f32_16x16x32_bf16 v[6:9], v[176:179], v[216:219], v[6:9]
	v_mfma_f32_16x16x32_bf16 v[6:9], v[180:183], v[220:223], v[6:9]
	v_mfma_f32_16x16x32_bf16 v[2:5], v[184:187], v[216:219], v[2:5]
	v_mfma_f32_16x16x32_bf16 v[2:5], v[188:191], v[220:223], v[2:5]
	s_barrier
	s_add_i32 s31, 0, 0x18000
	s_add_i32 s33, 0, 0x1c000
	ds_read_b128 v[152:155], v246
	ds_read_b128 v[164:167], v246 offset:1024
	ds_read_b128 v[168:171], v246 offset:2048
	ds_read_b128 v[172:175], v246 offset:3072
	ds_read_b128 v[176:179], v247
	ds_read_b128 v[180:183], v247 offset:1024
	ds_read_b128 v[184:187], v247 offset:2048
	ds_read_b128 v[188:191], v247 offset:3072
	s_add_u32 s98, s22, 0x80
	s_addc_u32 s99, s23, 0
	s_add_u32 s22, s22, 0x100000
	s_addc_u32 s23, s23, 0
	s_mov_b32 m0, s41
	ds_read_b128 v[192:195], v162 offset:32768
	ds_read_b128 v[196:199], v162 offset:33792
	ds_read_b128 v[200:203], v162 offset:34816
	ds_read_b128 v[204:207], v162 offset:35840
	ds_read_b128 v[208:211], v162 offset:36864
	ds_read_b128 v[212:215], v162 offset:37888
	ds_read_b128 v[216:219], v162 offset:38912
	ds_read_b128 v[220:223], v162 offset:39936
	global_load_lds_dwordx4 v130, s[22:23]
	s_mov_b32 m0, s42
	s_nop 0
	global_load_lds_dwordx4 v134, s[22:23]
	s_waitcnt vmcnt(8)
	s_waitcnt lgkmcnt(0)
	s_barrier
	v_mfma_f32_16x16x32_bf16 v[126:129], v[152:155], v[192:195], v[126:129]
	v_mfma_f32_16x16x32_bf16 v[126:129], v[164:167], v[196:199], v[126:129]
	v_mfma_f32_16x16x32_bf16 v[122:125], v[168:171], v[192:195], v[122:125]
	v_mfma_f32_16x16x32_bf16 v[122:125], v[172:175], v[196:199], v[122:125]
	v_mfma_f32_16x16x32_bf16 v[114:117], v[152:155], v[200:203], v[114:117]
	v_mfma_f32_16x16x32_bf16 v[114:117], v[164:167], v[204:207], v[114:117]
	v_mfma_f32_16x16x32_bf16 v[106:109], v[168:171], v[200:203], v[106:109]
	v_mfma_f32_16x16x32_bf16 v[106:109], v[172:175], v[204:207], v[106:109]
	v_mfma_f32_16x16x32_bf16 v[98:101], v[152:155], v[208:211], v[98:101]
	v_mfma_f32_16x16x32_bf16 v[98:101], v[164:167], v[212:215], v[98:101]
	v_mfma_f32_16x16x32_bf16 v[90:93], v[168:171], v[208:211], v[90:93]
	v_mfma_f32_16x16x32_bf16 v[90:93], v[172:175], v[212:215], v[90:93]
	v_mfma_f32_16x16x32_bf16 v[82:85], v[152:155], v[216:219], v[82:85]
	v_mfma_f32_16x16x32_bf16 v[82:85], v[164:167], v[220:223], v[82:85]
	v_mfma_f32_16x16x32_bf16 v[74:77], v[168:171], v[216:219], v[74:77]
	v_mfma_f32_16x16x32_bf16 v[74:77], v[172:175], v[220:223], v[74:77]
	v_mfma_f32_16x16x32_bf16 v[118:121], v[176:179], v[192:195], v[118:121]
	v_mfma_f32_16x16x32_bf16 v[118:121], v[180:183], v[196:199], v[118:121]
	v_mfma_f32_16x16x32_bf16 v[110:113], v[184:187], v[192:195], v[110:113]
	v_mfma_f32_16x16x32_bf16 v[110:113], v[188:191], v[196:199], v[110:113]
	v_mfma_f32_16x16x32_bf16 v[102:105], v[176:179], v[200:203], v[102:105]
	v_mfma_f32_16x16x32_bf16 v[102:105], v[180:183], v[204:207], v[102:105]
	v_mfma_f32_16x16x32_bf16 v[94:97], v[184:187], v[200:203], v[94:97]
	v_mfma_f32_16x16x32_bf16 v[94:97], v[188:191], v[204:207], v[94:97]
	v_mfma_f32_16x16x32_bf16 v[86:89], v[176:179], v[208:211], v[86:89]
	v_mfma_f32_16x16x32_bf16 v[86:89], v[180:183], v[212:215], v[86:89]
	v_mfma_f32_16x16x32_bf16 v[78:81], v[184:187], v[208:211], v[78:81]
	v_mfma_f32_16x16x32_bf16 v[78:81], v[188:191], v[212:215], v[78:81]
	v_mfma_f32_16x16x32_bf16 v[70:73], v[176:179], v[216:219], v[70:73]
	v_mfma_f32_16x16x32_bf16 v[70:73], v[180:183], v[220:223], v[70:73]
	v_mfma_f32_16x16x32_bf16 v[66:69], v[184:187], v[216:219], v[66:69]
	v_mfma_f32_16x16x32_bf16 v[66:69], v[188:191], v[220:223], v[66:69]
	s_barrier
	s_add_i32 s22, s31, s38
	s_mov_b32 m0, s22
	ds_read_b128 v[192:195], v162 offset:49152
	ds_read_b128 v[196:199], v162 offset:50176
	ds_read_b128 v[200:203], v162 offset:51200
	ds_read_b128 v[204:207], v162 offset:52224
	ds_read_b128 v[208:211], v162 offset:53248
	ds_read_b128 v[212:215], v162 offset:54272
	ds_read_b128 v[216:219], v162 offset:55296
	ds_read_b128 v[220:223], v162 offset:56320
	s_add_u32 s20, s20, 0x80
	s_addc_u32 s21, s21, 0
	global_load_lds_dwordx4 v132, s[20:21]
	s_add_i32 m0, s22, 0x2000
	s_add_i32 s22, s33, s38
	global_load_lds_dwordx4 v136, s[20:21]
	s_add_u32 s20, s20, 0x100000
	s_addc_u32 s21, s21, 0
	s_mov_b32 m0, s22
	s_nop 0
	global_load_lds_dwordx4 v132, s[20:21]
	s_add_i32 m0, s22, 0x2000
	s_nop 0
	global_load_lds_dwordx4 v136, s[20:21]
	s_mov_b32 m0, s45
	s_nop 0
	global_load_lds_dwordx4 v130, s[98:99]
	s_mov_b32 m0, s46
	s_nop 0
	global_load_lds_dwordx4 v134, s[98:99]
	s_waitcnt vmcnt(8)
	s_waitcnt lgkmcnt(0)
	s_barrier
	v_mfma_f32_16x16x32_bf16 v[62:65], v[152:155], v[192:195], v[62:65]
	v_mfma_f32_16x16x32_bf16 v[62:65], v[164:167], v[196:199], v[62:65]
	v_mfma_f32_16x16x32_bf16 v[58:61], v[168:171], v[192:195], v[58:61]
	v_mfma_f32_16x16x32_bf16 v[58:61], v[172:175], v[196:199], v[58:61]
	v_mfma_f32_16x16x32_bf16 v[46:49], v[152:155], v[200:203], v[46:49]
	v_mfma_f32_16x16x32_bf16 v[46:49], v[164:167], v[204:207], v[46:49]
	v_mfma_f32_16x16x32_bf16 v[42:45], v[168:171], v[200:203], v[42:45]
	v_mfma_f32_16x16x32_bf16 v[42:45], v[172:175], v[204:207], v[42:45]
	v_mfma_f32_16x16x32_bf16 v[30:33], v[152:155], v[208:211], v[30:33]
	v_mfma_f32_16x16x32_bf16 v[30:33], v[164:167], v[212:215], v[30:33]
	v_mfma_f32_16x16x32_bf16 v[26:29], v[168:171], v[208:211], v[26:29]
	v_mfma_f32_16x16x32_bf16 v[26:29], v[172:175], v[212:215], v[26:29]
	v_mfma_f32_16x16x32_bf16 v[14:17], v[152:155], v[216:219], v[14:17]
	v_mfma_f32_16x16x32_bf16 v[14:17], v[164:167], v[220:223], v[14:17]
	v_mfma_f32_16x16x32_bf16 v[10:13], v[168:171], v[216:219], v[10:13]
	v_mfma_f32_16x16x32_bf16 v[10:13], v[172:175], v[220:223], v[10:13]
	v_mfma_f32_16x16x32_bf16 v[54:57], v[176:179], v[192:195], v[54:57]
	v_mfma_f32_16x16x32_bf16 v[54:57], v[180:183], v[196:199], v[54:57]
	v_mfma_f32_16x16x32_bf16 v[50:53], v[184:187], v[192:195], v[50:53]
	v_mfma_f32_16x16x32_bf16 v[50:53], v[188:191], v[196:199], v[50:53]
	v_mfma_f32_16x16x32_bf16 v[38:41], v[176:179], v[200:203], v[38:41]
	v_mfma_f32_16x16x32_bf16 v[38:41], v[180:183], v[204:207], v[38:41]
	v_mfma_f32_16x16x32_bf16 v[34:37], v[184:187], v[200:203], v[34:37]
	v_mfma_f32_16x16x32_bf16 v[34:37], v[188:191], v[204:207], v[34:37]
	v_mfma_f32_16x16x32_bf16 v[22:25], v[176:179], v[208:211], v[22:25]
	v_mfma_f32_16x16x32_bf16 v[22:25], v[180:183], v[212:215], v[22:25]
	v_mfma_f32_16x16x32_bf16 v[18:21], v[184:187], v[208:211], v[18:21]
	v_mfma_f32_16x16x32_bf16 v[18:21], v[188:191], v[212:215], v[18:21]
	v_mfma_f32_16x16x32_bf16 v[6:9], v[176:179], v[216:219], v[6:9]
	v_mfma_f32_16x16x32_bf16 v[6:9], v[180:183], v[220:223], v[6:9]
	v_mfma_f32_16x16x32_bf16 v[2:5], v[184:187], v[216:219], v[2:5]
	v_mfma_f32_16x16x32_bf16 v[2:5], v[188:191], v[220:223], v[2:5]
	s_barrier
	s_add_i32 s30, s30, 2
	s_add_u32 s0, s0, 0x100
	s_addc_u32 s1, s1, 0
	s_add_u32 s27, s27, 0x100
	s_addc_u32 s29, s29, 0
	s_cmp_gt_u32 s30, 61
	s_cbranch_scc0 .LBB0_216
	s_setprio 0
	s_and_b64 vcc, exec, s[10:11]
	s_cbranch_vccz .LBB0_219
	s_barrier

.LBB0_270:
	s_ashr_i32 s13, s12, 31
	s_lshl_b64 s[14:15], s[12:13], 20
	s_add_u32 s14, s79, s14
	s_addc_u32 s15, s93, s15
	s_and_b64 s[16:17], s[2:3], exec
	s_cselect_b32 s13, s15, s21
	s_cselect_b32 s25, s14, s20
	s_ashr_i32 s11, s10, 31
	s_lshl_b64 s[16:17], s[10:11], 20
	s_add_u32 s16, s76, s16
	s_addc_u32 s17, s77, s17
	s_and_b64 s[22:23], s[2:3], exec
	s_cselect_b32 s11, s17, s1
	s_cselect_b32 s26, s16, s0
	s_add_u32 s20, s20, 0x80080
	s_addc_u32 s21, s21, 0
	s_add_u32 s27, s0, 0x100
	v_mov_b32_e32 v34, 0
	v_mov_b32_e32 v173, v163
	v_mov_b32_e32 v169, v163
	v_mov_b32_e32 v171, v163
	s_addc_u32 s28, s1, 0
	s_mov_b32 s29, -2
	v_mov_b64_e32 v[34:35], 0
	v_mov_b64_e32 v[36:37], 0
	v_mov_b64_e32 v[38:39], 0
	v_mov_b64_e32 v[40:41], 0
	v_mov_b64_e32 v[42:43], 0
	v_mov_b64_e32 v[44:45], 0
	v_mov_b64_e32 v[46:47], 0
	v_mov_b64_e32 v[48:49], 0
	v_mov_b64_e32 v[50:51], 0
	v_mov_b64_e32 v[52:53], 0
	v_mov_b64_e32 v[54:55], 0
	v_mov_b64_e32 v[56:57], 0
	v_mov_b64_e32 v[58:59], 0
	v_mov_b64_e32 v[60:61], 0
	v_mov_b64_e32 v[62:63], 0
	v_mov_b64_e32 v[64:65], 0
	v_mov_b64_e32 v[66:67], 0
	v_mov_b64_e32 v[68:69], 0
	v_mov_b64_e32 v[70:71], 0
	v_mov_b64_e32 v[72:73], 0
	v_mov_b64_e32 v[74:75], 0
	v_mov_b64_e32 v[76:77], 0
	v_mov_b64_e32 v[78:79], 0
	v_mov_b64_e32 v[80:81], 0
	v_mov_b64_e32 v[82:83], 0
	v_mov_b64_e32 v[84:85], 0
	v_mov_b64_e32 v[86:87], 0
	v_mov_b64_e32 v[88:89], 0
	v_mov_b64_e32 v[90:91], 0
	v_mov_b64_e32 v[92:93], 0
	v_mov_b64_e32 v[94:95], 0
	v_mov_b64_e32 v[96:97], 0
	v_mov_b64_e32 v[98:99], 0
	v_mov_b64_e32 v[100:101], 0
	v_mov_b64_e32 v[102:103], 0
	v_mov_b64_e32 v[104:105], 0
	v_mov_b64_e32 v[106:107], 0
	v_mov_b64_e32 v[108:109], 0
	v_mov_b64_e32 v[110:111], 0
	v_mov_b64_e32 v[112:113], 0
	v_mov_b64_e32 v[114:115], 0
	v_mov_b64_e32 v[116:117], 0
	v_mov_b64_e32 v[118:119], 0
	v_mov_b64_e32 v[120:121], 0
	v_mov_b64_e32 v[122:123], 0
	v_mov_b64_e32 v[124:125], 0
	v_mov_b64_e32 v[126:127], 0
	v_mov_b64_e32 v[128:129], 0
	v_mov_b64_e32 v[130:131], 0
	v_mov_b64_e32 v[132:133], 0
	v_mov_b64_e32 v[134:135], 0
	v_mov_b64_e32 v[136:137], 0
	v_mov_b64_e32 v[138:139], 0
	v_mov_b64_e32 v[140:141], 0
	v_mov_b64_e32 v[142:143], 0
	v_mov_b64_e32 v[144:145], 0
	v_mov_b64_e32 v[146:147], 0
	v_mov_b64_e32 v[148:149], 0
	v_mov_b64_e32 v[150:151], 0
	v_mov_b64_e32 v[152:153], 0
	v_mov_b64_e32 v[154:155], 0
	v_mov_b64_e32 v[156:157], 0
	v_mov_b64_e32 v[158:159], 0
	v_mov_b64_e32 v[160:161], 0
	v_add_u32_e32 v246, 0x18000, v182
	v_add_u32_e32 v247, 0x1c000, v182
	v_cmp_gt_u32_e32 vcc, 0x100, v0
	s_cbranch_vccnz .Lgprio_271
	s_setprio 1
.Lgprio_271:
.LBB0_271:
	ds_read_b128 v[26:29], v183
	ds_read_b128 v[30:33], v183 offset:1024
	ds_read_b128 v[18:21], v183 offset:2048
	ds_read_b128 v[22:25], v183 offset:3072
	ds_read_b128 v[10:13], v184
	ds_read_b128 v[14:17], v184 offset:1024
	ds_read_b128 v[2:5], v184 offset:2048
	ds_read_b128 v[6:9], v184 offset:3072
	s_add_u32 s0, s20, 0xfff80080
	s_addc_u32 s1, s21, -1
	s_cmp_eq_u32 s29, 28
	s_cselect_b32 s23, s13, s1
	s_cselect_b32 s22, s25, s0
	s_cselect_b32 s1, s11, s28
	s_cselect_b32 s0, s26, s27
	s_add_i32 m0, s19, 0xc000
	ds_read_b128 v[174:177], v185
	ds_read_b128 v[178:181], v185 offset:1024
	ds_read_b128 v[188:191], v185 offset:2048
	ds_read_b128 v[192:195], v185 offset:3072
	ds_read_b128 v[196:199], v185 offset:4096
	ds_read_b128 v[200:203], v185 offset:5120
	ds_read_b128 v[204:207], v185 offset:6144
	ds_read_b128 v[208:211], v185 offset:7168
	global_load_lds_dwordx4 v162, s[20:21]
	s_add_i32 m0, s19, 0xe000
	s_nop 0
	global_load_lds_dwordx4 v172, s[20:21]
	s_waitcnt vmcnt(8)
	s_waitcnt lgkmcnt(0)
	s_barrier
	v_mfma_f32_16x16x128_f8f6f4 v[158:161], v[26:33], v[174:181], v[158:161]
	v_mfma_f32_16x16x128_f8f6f4 v[154:157], v[18:25], v[174:181], v[154:157]
	v_mfma_f32_16x16x128_f8f6f4 v[146:149], v[26:33], v[188:195], v[146:149]
	v_mfma_f32_16x16x128_f8f6f4 v[138:141], v[18:25], v[188:195], v[138:141]
	v_mfma_f32_16x16x128_f8f6f4 v[130:133], v[26:33], v[196:203], v[130:133]
	v_mfma_f32_16x16x128_f8f6f4 v[122:125], v[18:25], v[196:203], v[122:125]
	v_mfma_f32_16x16x128_f8f6f4 v[114:117], v[26:33], v[204:211], v[114:117]
	v_mfma_f32_16x16x128_f8f6f4 v[106:109], v[18:25], v[204:211], v[106:109]
	v_mfma_f32_16x16x128_f8f6f4 v[150:153], v[10:17], v[174:181], v[150:153]
	v_mfma_f32_16x16x128_f8f6f4 v[142:145], v[2:9], v[174:181], v[142:145]
	v_mfma_f32_16x16x128_f8f6f4 v[134:137], v[10:17], v[188:195], v[134:137]
	v_mfma_f32_16x16x128_f8f6f4 v[126:129], v[2:9], v[188:195], v[126:129]
	v_mfma_f32_16x16x128_f8f6f4 v[118:121], v[10:17], v[196:203], v[118:121]
	v_mfma_f32_16x16x128_f8f6f4 v[110:113], v[2:9], v[196:203], v[110:113]
	v_mfma_f32_16x16x128_f8f6f4 v[102:105], v[10:17], v[204:211], v[102:105]
	v_mfma_f32_16x16x128_f8f6f4 v[98:101], v[2:9], v[204:211], v[98:101]
	s_barrier
	s_add_i32 s30, s48, s37
	s_mov_b32 m0, s30
	ds_read_b128 v[188:191], v185 offset:16384
	ds_read_b128 v[192:195], v185 offset:17408
	ds_read_b128 v[196:199], v185 offset:18432
	ds_read_b128 v[200:203], v185 offset:19456
	ds_read_b128 v[204:207], v185 offset:20480
	ds_read_b128 v[208:211], v185 offset:21504
	ds_read_b128 v[212:215], v185 offset:22528
	ds_read_b128 v[216:219], v185 offset:23552
	global_load_lds_dwordx4 v168, s[0:1]
	s_add_i32 m0, s30, 0x2000
	s_add_u32 s30, s0, 0x80000
	s_addc_u32 s31, s1, 0
	s_add_i32 s33, s49, s37
	global_load_lds_dwordx4 v170, s[0:1]
	s_mov_b32 m0, s33
	global_load_lds_dwordx4 v168, s[30:31]
	s_add_i32 m0, s33, 0x2000
	s_nop 0
	global_load_lds_dwordx4 v170, s[30:31]
	s_mov_b32 m0, s19
	s_nop 0
	global_load_lds_dwordx4 v162, s[22:23]
	s_mov_b32 m0, s38
	s_nop 0
	global_load_lds_dwordx4 v172, s[22:23]
	s_waitcnt vmcnt(8)
	s_waitcnt lgkmcnt(0)
	s_barrier
	v_mfma_f32_16x16x128_f8f6f4 v[94:97], v[26:33], v[188:195], v[94:97]
	v_mfma_f32_16x16x128_f8f6f4 v[90:93], v[18:25], v[188:195], v[90:93]
	v_mfma_f32_16x16x128_f8f6f4 v[78:81], v[26:33], v[196:203], v[78:81]
	v_mfma_f32_16x16x128_f8f6f4 v[74:77], v[18:25], v[196:203], v[74:77]
	v_mfma_f32_16x16x128_f8f6f4 v[62:65], v[26:33], v[204:211], v[62:65]
	v_mfma_f32_16x16x128_f8f6f4 v[58:61], v[18:25], v[204:211], v[58:61]
	v_mfma_f32_16x16x128_f8f6f4 v[46:49], v[26:33], v[212:219], v[46:49]
	v_mfma_f32_16x16x128_f8f6f4 v[42:45], v[18:25], v[212:219], v[42:45]
	v_mfma_f32_16x16x128_f8f6f4 v[86:89], v[10:17], v[188:195], v[86:89]
	v_mfma_f32_16x16x128_f8f6f4 v[82:85], v[2:9], v[188:195], v[82:85]
	v_mfma_f32_16x16x128_f8f6f4 v[70:73], v[10:17], v[196:203], v[70:73]
	v_mfma_f32_16x16x128_f8f6f4 v[66:69], v[2:9], v[196:203], v[66:69]
	v_mfma_f32_16x16x128_f8f6f4 v[54:57], v[10:17], v[204:211], v[54:57]
	v_mfma_f32_16x16x128_f8f6f4 v[50:53], v[2:9], v[204:211], v[50:53]
	v_mfma_f32_16x16x128_f8f6f4 v[38:41], v[10:17], v[212:219], v[38:41]
	v_mfma_f32_16x16x128_f8f6f4 v[34:37], v[2:9], v[212:219], v[34:37]
	s_barrier
	s_add_i32 s30, 0, 0x18000
	s_add_i32 s31, 0, 0x1c000
	ds_read_b128 v[2:5], v246
	ds_read_b128 v[6:9], v246 offset:1024
	ds_read_b128 v[10:13], v246 offset:2048
	ds_read_b128 v[14:17], v246 offset:3072
	ds_read_b128 v[18:21], v247
	ds_read_b128 v[22:25], v247 offset:1024
	ds_read_b128 v[26:29], v247 offset:2048
	ds_read_b128 v[30:33], v247 offset:3072
	s_add_u32 s98, s22, 0x80
	s_addc_u32 s99, s23, 0
	s_add_u32 s22, s22, 0x80000
	s_addc_u32 s23, s23, 0
	s_mov_b32 m0, s39
	ds_read_b128 v[188:191], v185 offset:32768
	ds_read_b128 v[192:195], v185 offset:33792
	ds_read_b128 v[196:199], v185 offset:34816
	ds_read_b128 v[200:203], v185 offset:35840
	ds_read_b128 v[204:207], v185 offset:36864
	ds_read_b128 v[208:211], v185 offset:37888
	ds_read_b128 v[212:215], v185 offset:38912
	ds_read_b128 v[216:219], v185 offset:39936
	global_load_lds_dwordx4 v162, s[22:23]
	s_mov_b32 m0, s40
	s_nop 0
	global_load_lds_dwordx4 v172, s[22:23]
	s_waitcnt vmcnt(8)
	s_waitcnt lgkmcnt(0)
	s_barrier
	v_mfma_f32_16x16x128_f8f6f4 v[158:161], v[2:9], v[188:195], v[158:161]
	v_mfma_f32_16x16x128_f8f6f4 v[154:157], v[10:17], v[188:195], v[154:157]
	v_mfma_f32_16x16x128_f8f6f4 v[146:149], v[2:9], v[196:203], v[146:149]
	v_mfma_f32_16x16x128_f8f6f4 v[138:141], v[10:17], v[196:203], v[138:141]
	v_mfma_f32_16x16x128_f8f6f4 v[130:133], v[2:9], v[204:211], v[130:133]
	v_mfma_f32_16x16x128_f8f6f4 v[122:125], v[10:17], v[204:211], v[122:125]
	v_mfma_f32_16x16x128_f8f6f4 v[114:117], v[2:9], v[212:219], v[114:117]
	v_mfma_f32_16x16x128_f8f6f4 v[106:109], v[10:17], v[212:219], v[106:109]
	v_mfma_f32_16x16x128_f8f6f4 v[150:153], v[18:25], v[188:195], v[150:153]
	v_mfma_f32_16x16x128_f8f6f4 v[142:145], v[26:33], v[188:195], v[142:145]
	v_mfma_f32_16x16x128_f8f6f4 v[134:137], v[18:25], v[196:203], v[134:137]
	v_mfma_f32_16x16x128_f8f6f4 v[126:129], v[26:33], v[196:203], v[126:129]
	v_mfma_f32_16x16x128_f8f6f4 v[118:121], v[18:25], v[204:211], v[118:121]
	v_mfma_f32_16x16x128_f8f6f4 v[110:113], v[26:33], v[204:211], v[110:113]
	v_mfma_f32_16x16x128_f8f6f4 v[102:105], v[18:25], v[212:219], v[102:105]
	v_mfma_f32_16x16x128_f8f6f4 v[98:101], v[26:33], v[212:219], v[98:101]
	s_barrier
	s_add_i32 s22, s30, s37
	s_mov_b32 m0, s22
	ds_read_b128 v[188:191], v185 offset:49152
	ds_read_b128 v[192:195], v185 offset:50176
	ds_read_b128 v[196:199], v185 offset:51200
	ds_read_b128 v[200:203], v185 offset:52224
	ds_read_b128 v[204:207], v185 offset:53248
	ds_read_b128 v[208:211], v185 offset:54272
	ds_read_b128 v[212:215], v185 offset:55296
	ds_read_b128 v[216:219], v185 offset:56320
	s_add_u32 s0, s0, 0x80
	s_addc_u32 s1, s1, 0
	global_load_lds_dwordx4 v168, s[0:1]
	s_add_i32 m0, s22, 0x2000
	s_add_i32 s22, s31, s37
	global_load_lds_dwordx4 v170, s[0:1]
	s_add_u32 s0, s0, 0x80000
	s_addc_u32 s1, s1, 0
	s_mov_b32 m0, s22
	s_nop 0
	global_load_lds_dwordx4 v168, s[0:1]
	s_add_i32 m0, s22, 0x2000
	s_nop 0
	global_load_lds_dwordx4 v170, s[0:1]
	s_mov_b32 m0, s44
	s_nop 0
	global_load_lds_dwordx4 v162, s[98:99]
	s_mov_b32 m0, s45
	s_nop 0
	global_load_lds_dwordx4 v172, s[98:99]
	s_waitcnt vmcnt(8)
	s_waitcnt lgkmcnt(0)
	s_barrier
	v_mfma_f32_16x16x128_f8f6f4 v[94:97], v[2:9], v[188:195], v[94:97]
	v_mfma_f32_16x16x128_f8f6f4 v[90:93], v[10:17], v[188:195], v[90:93]
	v_mfma_f32_16x16x128_f8f6f4 v[78:81], v[2:9], v[196:203], v[78:81]
	v_mfma_f32_16x16x128_f8f6f4 v[74:77], v[10:17], v[196:203], v[74:77]
	v_mfma_f32_16x16x128_f8f6f4 v[62:65], v[2:9], v[204:211], v[62:65]
	v_mfma_f32_16x16x128_f8f6f4 v[58:61], v[10:17], v[204:211], v[58:61]
	v_mfma_f32_16x16x128_f8f6f4 v[46:49], v[2:9], v[212:219], v[46:49]
	v_mfma_f32_16x16x128_f8f6f4 v[42:45], v[10:17], v[212:219], v[42:45]
	v_mfma_f32_16x16x128_f8f6f4 v[86:89], v[18:25], v[188:195], v[86:89]
	v_mfma_f32_16x16x128_f8f6f4 v[82:85], v[26:33], v[188:195], v[82:85]
	v_mfma_f32_16x16x128_f8f6f4 v[70:73], v[18:25], v[196:203], v[70:73]
	v_mfma_f32_16x16x128_f8f6f4 v[66:69], v[26:33], v[196:203], v[66:69]
	v_mfma_f32_16x16x128_f8f6f4 v[54:57], v[18:25], v[204:211], v[54:57]
	v_mfma_f32_16x16x128_f8f6f4 v[50:53], v[26:33], v[204:211], v[50:53]
	v_mfma_f32_16x16x128_f8f6f4 v[38:41], v[18:25], v[212:219], v[38:41]
	v_mfma_f32_16x16x128_f8f6f4 v[34:37], v[26:33], v[212:219], v[34:37]
	s_barrier
	s_add_i32 s29, s29, 2
	s_add_u32 s20, s20, 0x100
	s_addc_u32 s21, s21, 0
	s_add_u32 s27, s27, 0x100
	s_addc_u32 s28, s28, 0
	s_cmp_gt_u32 s29, 29
	s_cbranch_scc0 .LBB0_271
	s_setprio 0
	s_and_b64 vcc, exec, s[8:9]
	s_cbranch_vccz .LBB0_274
	s_barrier

.LBB0_838:
	s_ashr_i32 s21, s20, 31
	s_lshl_b64 s[22:23], s[20:21], 19
	s_add_u32 s22, s68, s22
	s_addc_u32 s23, s69, s23
	s_and_b64 s[24:25], s[2:3], exec
	s_cselect_b32 s21, s23, s29
	s_cselect_b32 s49, s22, s28
	s_ashr_i32 s19, s18, 31
	s_lshl_b64 s[24:25], s[18:19], 19
	v_readlane_b32 s34, v245, 14
	v_readlane_b32 s35, v245, 15
	s_add_u32 s24, s34, s24
	s_addc_u32 s25, s35, s25
	s_and_b64 s[34:35], s[2:3], exec
	s_cselect_b32 s19, s25, s31
	s_cselect_b32 s50, s24, s30
	s_add_u32 s28, s28, 0x40080
	s_addc_u32 s29, s29, 0
	s_add_u32 s51, s30, 0x100
	v_mov_b32_e32 v34, 0
	v_mov_b32_e32 v173, v163
	v_mov_b32_e32 v169, v163
	v_mov_b32_e32 v171, v163
	s_addc_u32 s52, s31, 0
	s_mov_b32 s53, -2
	v_mov_b64_e32 v[34:35], 0
	v_mov_b64_e32 v[36:37], 0
	v_mov_b64_e32 v[38:39], 0
	v_mov_b64_e32 v[40:41], 0
	v_mov_b64_e32 v[42:43], 0
	v_mov_b64_e32 v[44:45], 0
	v_mov_b64_e32 v[46:47], 0
	v_mov_b64_e32 v[48:49], 0
	v_mov_b64_e32 v[50:51], 0
	v_mov_b64_e32 v[52:53], 0
	v_mov_b64_e32 v[54:55], 0
	v_mov_b64_e32 v[56:57], 0
	v_mov_b64_e32 v[58:59], 0
	v_mov_b64_e32 v[60:61], 0
	v_mov_b64_e32 v[62:63], 0
	v_mov_b64_e32 v[64:65], 0
	v_mov_b64_e32 v[66:67], 0
	v_mov_b64_e32 v[68:69], 0
	v_mov_b64_e32 v[70:71], 0
	v_mov_b64_e32 v[72:73], 0
	v_mov_b64_e32 v[74:75], 0
	v_mov_b64_e32 v[76:77], 0
	v_mov_b64_e32 v[78:79], 0
	v_mov_b64_e32 v[80:81], 0
	v_mov_b64_e32 v[82:83], 0
	v_mov_b64_e32 v[84:85], 0
	v_mov_b64_e32 v[86:87], 0
	v_mov_b64_e32 v[88:89], 0
	v_mov_b64_e32 v[90:91], 0
	v_mov_b64_e32 v[92:93], 0
	v_mov_b64_e32 v[94:95], 0
	v_mov_b64_e32 v[96:97], 0
	s_waitcnt vmcnt(0)
	v_mov_b64_e32 v[98:99], 0
	v_mov_b64_e32 v[100:101], 0
	v_mov_b64_e32 v[102:103], 0
	v_mov_b64_e32 v[104:105], 0
	v_mov_b64_e32 v[106:107], 0
	v_mov_b64_e32 v[108:109], 0
	v_mov_b64_e32 v[110:111], 0
	v_mov_b64_e32 v[112:113], 0
	v_mov_b64_e32 v[114:115], 0
	v_mov_b64_e32 v[116:117], 0
	v_mov_b64_e32 v[118:119], 0
	v_mov_b64_e32 v[120:121], 0
	v_mov_b64_e32 v[122:123], 0
	v_mov_b64_e32 v[124:125], 0
	v_mov_b64_e32 v[126:127], 0
	v_mov_b64_e32 v[128:129], 0
	v_mov_b64_e32 v[130:131], 0
	v_mov_b64_e32 v[132:133], 0
	v_mov_b64_e32 v[134:135], 0
	v_mov_b64_e32 v[136:137], 0
	v_mov_b64_e32 v[138:139], 0
	v_mov_b64_e32 v[140:141], 0
	v_mov_b64_e32 v[142:143], 0
	v_mov_b64_e32 v[144:145], 0
	v_mov_b64_e32 v[146:147], 0
	v_mov_b64_e32 v[148:149], 0
	v_mov_b64_e32 v[150:151], 0
	v_mov_b64_e32 v[152:153], 0
	v_mov_b64_e32 v[154:155], 0
	v_mov_b64_e32 v[156:157], 0
	v_mov_b64_e32 v[158:159], 0
	v_mov_b64_e32 v[160:161], 0
	v_add_u32_e32 v246, 0x18000, v182
	v_add_u32_e32 v247, 0x1c000, v182
	v_cmp_gt_u32_e32 vcc, 0x100, v0
	s_cbranch_vccnz .Lgprio_839
	s_setprio 1
.Lgprio_839:
.LBB0_839:
	ds_read_b128 v[26:29], v183
	ds_read_b128 v[30:33], v183 offset:1024
	ds_read_b128 v[18:21], v183 offset:2048
	ds_read_b128 v[22:25], v183 offset:3072
	ds_read_b128 v[10:13], v184
	ds_read_b128 v[14:17], v184 offset:1024
	ds_read_b128 v[2:5], v184 offset:2048
	ds_read_b128 v[6:9], v184 offset:3072
	s_add_u32 s30, s28, 0xfffc0080
	s_addc_u32 s31, s29, -1
	s_cmp_eq_u32 s53, 12
	s_cselect_b32 s35, s21, s31
	s_cselect_b32 s34, s49, s30
	s_cselect_b32 s31, s19, s52
	s_cselect_b32 s30, s50, s51
	s_add_i32 m0, s27, 0xc000
	ds_read_b128 v[174:177], v185
	ds_read_b128 v[178:181], v185 offset:1024
	ds_read_b128 v[188:191], v185 offset:2048
	ds_read_b128 v[192:195], v185 offset:3072
	ds_read_b128 v[196:199], v185 offset:4096
	ds_read_b128 v[200:203], v185 offset:5120
	ds_read_b128 v[204:207], v185 offset:6144
	ds_read_b128 v[208:211], v185 offset:7168
	global_load_lds_dwordx4 v162, s[28:29]
	s_add_i32 m0, s27, 0xe000
	s_nop 0
	global_load_lds_dwordx4 v172, s[28:29]
	s_waitcnt vmcnt(8)
	s_waitcnt lgkmcnt(0)
	s_barrier
	v_mfma_f32_16x16x128_f8f6f4 v[158:161], v[26:33], v[174:181], v[158:161]
	v_mfma_f32_16x16x128_f8f6f4 v[154:157], v[18:25], v[174:181], v[154:157]
	v_mfma_f32_16x16x128_f8f6f4 v[142:145], v[26:33], v[188:195], v[142:145]
	v_mfma_f32_16x16x128_f8f6f4 v[138:141], v[18:25], v[188:195], v[138:141]
	v_mfma_f32_16x16x128_f8f6f4 v[126:129], v[26:33], v[196:203], v[126:129]
	v_mfma_f32_16x16x128_f8f6f4 v[122:125], v[18:25], v[196:203], v[122:125]
	v_mfma_f32_16x16x128_f8f6f4 v[110:113], v[26:33], v[204:211], v[110:113]
	v_mfma_f32_16x16x128_f8f6f4 v[106:109], v[18:25], v[204:211], v[106:109]
	v_mfma_f32_16x16x128_f8f6f4 v[150:153], v[10:17], v[174:181], v[150:153]
	v_mfma_f32_16x16x128_f8f6f4 v[146:149], v[2:9], v[174:181], v[146:149]
	v_mfma_f32_16x16x128_f8f6f4 v[134:137], v[10:17], v[188:195], v[134:137]
	v_mfma_f32_16x16x128_f8f6f4 v[130:133], v[2:9], v[188:195], v[130:133]
	v_mfma_f32_16x16x128_f8f6f4 v[118:121], v[10:17], v[196:203], v[118:121]
	v_mfma_f32_16x16x128_f8f6f4 v[114:117], v[2:9], v[196:203], v[114:117]
	v_mfma_f32_16x16x128_f8f6f4 v[102:105], v[10:17], v[204:211], v[102:105]
	v_mfma_f32_16x16x128_f8f6f4 v[98:101], v[2:9], v[204:211], v[98:101]
	s_barrier
	s_add_i32 s54, s46, s36
	s_mov_b32 m0, s54
	ds_read_b128 v[188:191], v185 offset:16384
	ds_read_b128 v[192:195], v185 offset:17408
	ds_read_b128 v[196:199], v185 offset:18432
	ds_read_b128 v[200:203], v185 offset:19456
	ds_read_b128 v[204:207], v185 offset:20480
	ds_read_b128 v[208:211], v185 offset:21504
	ds_read_b128 v[212:215], v185 offset:22528
	ds_read_b128 v[216:219], v185 offset:23552
	global_load_lds_dwordx4 v168, s[30:31]
	s_add_i32 m0, s54, 0x2000
	s_add_u32 s54, s30, 0x40000
	s_addc_u32 s55, s31, 0
	s_add_i32 s56, s47, s36
	global_load_lds_dwordx4 v170, s[30:31]
	s_mov_b32 m0, s56
	global_load_lds_dwordx4 v168, s[54:55]
	s_add_i32 m0, s56, 0x2000
	s_nop 0
	global_load_lds_dwordx4 v170, s[54:55]
	s_mov_b32 m0, s27
	s_nop 0
	global_load_lds_dwordx4 v162, s[34:35]
	s_mov_b32 m0, s37
	s_nop 0
	global_load_lds_dwordx4 v172, s[34:35]
	s_waitcnt vmcnt(8)
	s_waitcnt lgkmcnt(0)
	s_barrier
	v_mfma_f32_16x16x128_f8f6f4 v[94:97], v[26:33], v[188:195], v[94:97]
	v_mfma_f32_16x16x128_f8f6f4 v[90:93], v[18:25], v[188:195], v[90:93]
	v_mfma_f32_16x16x128_f8f6f4 v[78:81], v[26:33], v[196:203], v[78:81]
	v_mfma_f32_16x16x128_f8f6f4 v[74:77], v[18:25], v[196:203], v[74:77]
	v_mfma_f32_16x16x128_f8f6f4 v[62:65], v[26:33], v[204:211], v[62:65]
	v_mfma_f32_16x16x128_f8f6f4 v[58:61], v[18:25], v[204:211], v[58:61]
	v_mfma_f32_16x16x128_f8f6f4 v[46:49], v[26:33], v[212:219], v[46:49]
	v_mfma_f32_16x16x128_f8f6f4 v[42:45], v[18:25], v[212:219], v[42:45]
	v_mfma_f32_16x16x128_f8f6f4 v[86:89], v[10:17], v[188:195], v[86:89]
	v_mfma_f32_16x16x128_f8f6f4 v[82:85], v[2:9], v[188:195], v[82:85]
	v_mfma_f32_16x16x128_f8f6f4 v[70:73], v[10:17], v[196:203], v[70:73]
	v_mfma_f32_16x16x128_f8f6f4 v[66:69], v[2:9], v[196:203], v[66:69]
	v_mfma_f32_16x16x128_f8f6f4 v[54:57], v[10:17], v[204:211], v[54:57]
	v_mfma_f32_16x16x128_f8f6f4 v[50:53], v[2:9], v[204:211], v[50:53]
	v_mfma_f32_16x16x128_f8f6f4 v[38:41], v[10:17], v[212:219], v[38:41]
	v_mfma_f32_16x16x128_f8f6f4 v[34:37], v[2:9], v[212:219], v[34:37]
	s_barrier
	s_add_i32 s54, 0, 0x18000
	s_add_i32 s55, 0, 0x1c000
	ds_read_b128 v[2:5], v246
	ds_read_b128 v[6:9], v246 offset:1024
	ds_read_b128 v[10:13], v246 offset:2048
	ds_read_b128 v[14:17], v246 offset:3072
	ds_read_b128 v[18:21], v247
	ds_read_b128 v[22:25], v247 offset:1024
	ds_read_b128 v[26:29], v247 offset:2048
	ds_read_b128 v[30:33], v247 offset:3072
	s_add_u32 s98, s34, 0x80
	s_addc_u32 s99, s35, 0
	s_add_u32 s34, s34, 0x40000
	s_addc_u32 s35, s35, 0
	s_mov_b32 m0, s38
	ds_read_b128 v[188:191], v185 offset:32768
	ds_read_b128 v[192:195], v185 offset:33792
	ds_read_b128 v[196:199], v185 offset:34816
	ds_read_b128 v[200:203], v185 offset:35840
	ds_read_b128 v[204:207], v185 offset:36864
	ds_read_b128 v[208:211], v185 offset:37888
	ds_read_b128 v[212:215], v185 offset:38912
	ds_read_b128 v[216:219], v185 offset:39936
	global_load_lds_dwordx4 v162, s[34:35]
	s_mov_b32 m0, s39
	s_nop 0
	global_load_lds_dwordx4 v172, s[34:35]
	s_waitcnt vmcnt(8)
	s_waitcnt lgkmcnt(0)
	s_barrier
	v_mfma_f32_16x16x128_f8f6f4 v[158:161], v[2:9], v[188:195], v[158:161]
	v_mfma_f32_16x16x128_f8f6f4 v[154:157], v[10:17], v[188:195], v[154:157]
	v_mfma_f32_16x16x128_f8f6f4 v[142:145], v[2:9], v[196:203], v[142:145]
	v_mfma_f32_16x16x128_f8f6f4 v[138:141], v[10:17], v[196:203], v[138:141]
	v_mfma_f32_16x16x128_f8f6f4 v[126:129], v[2:9], v[204:211], v[126:129]
	v_mfma_f32_16x16x128_f8f6f4 v[122:125], v[10:17], v[204:211], v[122:125]
	v_mfma_f32_16x16x128_f8f6f4 v[110:113], v[2:9], v[212:219], v[110:113]
	v_mfma_f32_16x16x128_f8f6f4 v[106:109], v[10:17], v[212:219], v[106:109]
	v_mfma_f32_16x16x128_f8f6f4 v[150:153], v[18:25], v[188:195], v[150:153]
	v_mfma_f32_16x16x128_f8f6f4 v[146:149], v[26:33], v[188:195], v[146:149]
	v_mfma_f32_16x16x128_f8f6f4 v[134:137], v[18:25], v[196:203], v[134:137]
	v_mfma_f32_16x16x128_f8f6f4 v[130:133], v[26:33], v[196:203], v[130:133]
	v_mfma_f32_16x16x128_f8f6f4 v[118:121], v[18:25], v[204:211], v[118:121]
	v_mfma_f32_16x16x128_f8f6f4 v[114:117], v[26:33], v[204:211], v[114:117]
	v_mfma_f32_16x16x128_f8f6f4 v[102:105], v[18:25], v[212:219], v[102:105]
	v_mfma_f32_16x16x128_f8f6f4 v[98:101], v[26:33], v[212:219], v[98:101]
	s_barrier
	s_add_i32 s34, s54, s36
	s_mov_b32 m0, s34
	ds_read_b128 v[188:191], v185 offset:49152
	ds_read_b128 v[192:195], v185 offset:50176
	ds_read_b128 v[196:199], v185 offset:51200
	ds_read_b128 v[200:203], v185 offset:52224
	ds_read_b128 v[204:207], v185 offset:53248
	ds_read_b128 v[208:211], v185 offset:54272
	ds_read_b128 v[212:215], v185 offset:55296
	ds_read_b128 v[216:219], v185 offset:56320
	s_add_u32 s30, s30, 0x80
	s_addc_u32 s31, s31, 0
	global_load_lds_dwordx4 v168, s[30:31]
	s_add_i32 m0, s34, 0x2000
	s_add_i32 s34, s55, s36
	global_load_lds_dwordx4 v170, s[30:31]
	s_add_u32 s30, s30, 0x40000
	s_addc_u32 s31, s31, 0
	s_mov_b32 m0, s34
	s_nop 0
	global_load_lds_dwordx4 v168, s[30:31]
	s_add_i32 m0, s34, 0x2000
	s_nop 0
	global_load_lds_dwordx4 v170, s[30:31]
	s_mov_b32 m0, s43
	s_nop 0
	global_load_lds_dwordx4 v162, s[98:99]
	s_mov_b32 m0, s44
	s_nop 0
	global_load_lds_dwordx4 v172, s[98:99]
	s_waitcnt vmcnt(8)
	s_waitcnt lgkmcnt(0)
	s_barrier
	v_mfma_f32_16x16x128_f8f6f4 v[94:97], v[2:9], v[188:195], v[94:97]
	v_mfma_f32_16x16x128_f8f6f4 v[90:93], v[10:17], v[188:195], v[90:93]
	v_mfma_f32_16x16x128_f8f6f4 v[78:81], v[2:9], v[196:203], v[78:81]
	v_mfma_f32_16x16x128_f8f6f4 v[74:77], v[10:17], v[196:203], v[74:77]
	v_mfma_f32_16x16x128_f8f6f4 v[62:65], v[2:9], v[204:211], v[62:65]
	v_mfma_f32_16x16x128_f8f6f4 v[58:61], v[10:17], v[204:211], v[58:61]
	v_mfma_f32_16x16x128_f8f6f4 v[46:49], v[2:9], v[212:219], v[46:49]
	v_mfma_f32_16x16x128_f8f6f4 v[42:45], v[10:17], v[212:219], v[42:45]
	v_mfma_f32_16x16x128_f8f6f4 v[86:89], v[18:25], v[188:195], v[86:89]
	v_mfma_f32_16x16x128_f8f6f4 v[82:85], v[26:33], v[188:195], v[82:85]
	v_mfma_f32_16x16x128_f8f6f4 v[70:73], v[18:25], v[196:203], v[70:73]
	v_mfma_f32_16x16x128_f8f6f4 v[66:69], v[26:33], v[196:203], v[66:69]
	v_mfma_f32_16x16x128_f8f6f4 v[54:57], v[18:25], v[204:211], v[54:57]
	v_mfma_f32_16x16x128_f8f6f4 v[50:53], v[26:33], v[204:211], v[50:53]
	v_mfma_f32_16x16x128_f8f6f4 v[38:41], v[18:25], v[212:219], v[38:41]
	v_mfma_f32_16x16x128_f8f6f4 v[34:37], v[26:33], v[212:219], v[34:37]
	s_barrier
	s_add_i32 s53, s53, 2
	s_add_u32 s28, s28, 0x100
	s_addc_u32 s29, s29, 0
	s_add_u32 s51, s51, 0x100
	s_addc_u32 s52, s52, 0
	s_cmp_gt_u32 s53, 13
	s_cbranch_scc0 .LBB0_839
	s_setprio 0
	s_and_b64 vcc, exec, s[10:11]
	s_cbranch_vccz .LBB0_842
	s_barrier

.LBB0_862:
	s_ashr_i32 s13, s12, 31
	s_lshl_b64 s[14:15], s[12:13], 20
	s_add_u32 s14, s62, s14
	s_addc_u32 s15, s63, s15
	s_and_b64 s[16:17], s[2:3], exec
	s_cselect_b32 s13, s15, s21
	s_cselect_b32 s39, s14, s20
	s_ashr_i32 s11, s10, 31
	s_lshl_b64 s[16:17], s[10:11], 20
	v_readlane_b32 s24, v245, 16
	v_readlane_b32 s25, v245, 17
	s_add_u32 s16, s24, s16
	s_addc_u32 s17, s25, s17
	s_and_b64 s[24:25], s[2:3], exec
	s_cselect_b32 s11, s17, s23
	s_cselect_b32 s40, s16, s22
	s_add_u32 s20, s20, 0x80080
	s_addc_u32 s21, s21, 0
	s_add_u32 s41, s22, 0x100
	v_mov_b32_e32 v2, 0
	s_addc_u32 s42, s23, 0
	s_mov_b32 s43, -2
	v_mov_b64_e32 v[2:3], 0
	v_mov_b64_e32 v[4:5], 0
	v_mov_b64_e32 v[6:7], 0
	v_mov_b64_e32 v[8:9], 0
	v_mov_b64_e32 v[10:11], 0
	v_mov_b64_e32 v[12:13], 0
	v_mov_b64_e32 v[14:15], 0
	v_mov_b64_e32 v[16:17], 0
	v_mov_b64_e32 v[18:19], 0
	v_mov_b64_e32 v[20:21], 0
	v_mov_b64_e32 v[22:23], 0
	v_mov_b64_e32 v[24:25], 0
	v_mov_b64_e32 v[26:27], 0
	v_mov_b64_e32 v[28:29], 0
	v_mov_b64_e32 v[30:31], 0
	v_mov_b64_e32 v[32:33], 0
	v_mov_b64_e32 v[34:35], 0
	v_mov_b64_e32 v[36:37], 0
	v_mov_b64_e32 v[38:39], 0
	v_mov_b64_e32 v[40:41], 0
	v_mov_b64_e32 v[42:43], 0
	v_mov_b64_e32 v[44:45], 0
	v_mov_b64_e32 v[46:47], 0
	v_mov_b64_e32 v[48:49], 0
	v_mov_b64_e32 v[50:51], 0
	v_mov_b64_e32 v[52:53], 0
	v_mov_b64_e32 v[54:55], 0
	v_mov_b64_e32 v[56:57], 0
	v_mov_b64_e32 v[58:59], 0
	v_mov_b64_e32 v[60:61], 0
	v_mov_b64_e32 v[62:63], 0
	v_mov_b64_e32 v[64:65], 0
	v_mov_b64_e32 v[66:67], 0
	v_mov_b64_e32 v[68:69], 0
	v_mov_b64_e32 v[70:71], 0
	v_mov_b64_e32 v[72:73], 0
	v_mov_b64_e32 v[74:75], 0
	v_mov_b64_e32 v[76:77], 0
	v_mov_b64_e32 v[78:79], 0
	v_mov_b64_e32 v[80:81], 0
	v_mov_b64_e32 v[82:83], 0
	v_mov_b64_e32 v[84:85], 0
	v_mov_b64_e32 v[86:87], 0
	v_mov_b64_e32 v[88:89], 0
	v_mov_b64_e32 v[90:91], 0
	v_mov_b64_e32 v[92:93], 0
	v_mov_b64_e32 v[94:95], 0
	v_mov_b64_e32 v[96:97], 0
	v_mov_b64_e32 v[98:99], 0
	v_mov_b64_e32 v[100:101], 0
	v_mov_b64_e32 v[102:103], 0
	v_mov_b64_e32 v[104:105], 0
	v_mov_b64_e32 v[106:107], 0
	v_mov_b64_e32 v[108:109], 0
	v_mov_b64_e32 v[110:111], 0
	v_mov_b64_e32 v[112:113], 0
	v_mov_b64_e32 v[114:115], 0
	v_mov_b64_e32 v[116:117], 0
	v_mov_b64_e32 v[118:119], 0
	v_mov_b64_e32 v[120:121], 0
	v_mov_b64_e32 v[122:123], 0
	v_mov_b64_e32 v[124:125], 0
	v_mov_b64_e32 v[126:127], 0
	v_mov_b64_e32 v[128:129], 0
	v_add_u32_e32 v246, 0x18000, v152
	v_add_u32_e32 v247, 0x1c000, v152
	v_cmp_gt_u32_e32 vcc, 0x100, v0
	s_cbranch_vccnz .Lgprio_863
	s_setprio 1
.Lgprio_863:
.LBB0_863:
	ds_read_b128 v[146:149], v154
	ds_read_b128 v[158:161], v154 offset:1024
	ds_read_b128 v[162:165], v154 offset:2048
	ds_read_b128 v[166:169], v154 offset:3072
	ds_read_b128 v[170:173], v155
	ds_read_b128 v[174:177], v155 offset:1024
	ds_read_b128 v[178:181], v155 offset:2048
	ds_read_b128 v[182:185], v155 offset:3072
	s_add_u32 s22, s20, 0xfff80080
	s_addc_u32 s23, s21, -1
	s_cmp_eq_u32 s43, 28
	s_cselect_b32 s25, s13, s23
	s_cselect_b32 s24, s39, s22
	s_cselect_b32 s23, s11, s42
	s_cselect_b32 s22, s40, s41
	s_add_i32 m0, s19, 0xc000
	ds_read_b128 v[186:189], v156
	ds_read_b128 v[190:193], v156 offset:1024
	ds_read_b128 v[194:197], v156 offset:2048
	ds_read_b128 v[198:201], v156 offset:3072
	ds_read_b128 v[202:205], v156 offset:4096
	ds_read_b128 v[206:209], v156 offset:5120
	ds_read_b128 v[210:213], v156 offset:6144
	ds_read_b128 v[214:217], v156 offset:7168
	global_load_lds_dwordx4 v138, s[20:21]
	s_add_i32 m0, s19, 0xe000
	s_nop 0
	global_load_lds_dwordx4 v140, s[20:21]
	s_waitcnt vmcnt(8)
	s_waitcnt lgkmcnt(0)
	s_barrier
	v_mfma_f32_16x16x32_bf16 v[126:129], v[146:149], v[186:189], v[126:129]
	v_mfma_f32_16x16x32_bf16 v[126:129], v[158:161], v[190:193], v[126:129]
	v_mfma_f32_16x16x32_bf16 v[122:125], v[162:165], v[186:189], v[122:125]
	v_mfma_f32_16x16x32_bf16 v[122:125], v[166:169], v[190:193], v[122:125]
	v_mfma_f32_16x16x32_bf16 v[110:113], v[146:149], v[194:197], v[110:113]
	v_mfma_f32_16x16x32_bf16 v[110:113], v[158:161], v[198:201], v[110:113]
	v_mfma_f32_16x16x32_bf16 v[106:109], v[162:165], v[194:197], v[106:109]
	v_mfma_f32_16x16x32_bf16 v[106:109], v[166:169], v[198:201], v[106:109]
	v_mfma_f32_16x16x32_bf16 v[94:97], v[146:149], v[202:205], v[94:97]
	v_mfma_f32_16x16x32_bf16 v[94:97], v[158:161], v[206:209], v[94:97]
	v_mfma_f32_16x16x32_bf16 v[90:93], v[162:165], v[202:205], v[90:93]
	v_mfma_f32_16x16x32_bf16 v[90:93], v[166:169], v[206:209], v[90:93]
	v_mfma_f32_16x16x32_bf16 v[78:81], v[146:149], v[210:213], v[78:81]
	v_mfma_f32_16x16x32_bf16 v[78:81], v[158:161], v[214:217], v[78:81]
	v_mfma_f32_16x16x32_bf16 v[74:77], v[162:165], v[210:213], v[74:77]
	v_mfma_f32_16x16x32_bf16 v[74:77], v[166:169], v[214:217], v[74:77]
	v_mfma_f32_16x16x32_bf16 v[118:121], v[170:173], v[186:189], v[118:121]
	v_mfma_f32_16x16x32_bf16 v[118:121], v[174:177], v[190:193], v[118:121]
	v_mfma_f32_16x16x32_bf16 v[114:117], v[178:181], v[186:189], v[114:117]
	v_mfma_f32_16x16x32_bf16 v[114:117], v[182:185], v[190:193], v[114:117]
	v_mfma_f32_16x16x32_bf16 v[102:105], v[170:173], v[194:197], v[102:105]
	v_mfma_f32_16x16x32_bf16 v[102:105], v[174:177], v[198:201], v[102:105]
	v_mfma_f32_16x16x32_bf16 v[98:101], v[178:181], v[194:197], v[98:101]
	v_mfma_f32_16x16x32_bf16 v[98:101], v[182:185], v[198:201], v[98:101]
	v_mfma_f32_16x16x32_bf16 v[86:89], v[170:173], v[202:205], v[86:89]
	v_mfma_f32_16x16x32_bf16 v[86:89], v[174:177], v[206:209], v[86:89]
	v_mfma_f32_16x16x32_bf16 v[82:85], v[178:181], v[202:205], v[82:85]
	v_mfma_f32_16x16x32_bf16 v[82:85], v[182:185], v[206:209], v[82:85]
	v_mfma_f32_16x16x32_bf16 v[70:73], v[170:173], v[210:213], v[70:73]
	v_mfma_f32_16x16x32_bf16 v[70:73], v[174:177], v[214:217], v[70:73]
	v_mfma_f32_16x16x32_bf16 v[66:69], v[178:181], v[210:213], v[66:69]
	v_mfma_f32_16x16x32_bf16 v[66:69], v[182:185], v[214:217], v[66:69]
	s_barrier
	s_add_i32 s44, s36, s27
	s_mov_b32 m0, s44
	ds_read_b128 v[186:189], v156 offset:16384
	ds_read_b128 v[190:193], v156 offset:17408
	ds_read_b128 v[194:197], v156 offset:18432
	ds_read_b128 v[198:201], v156 offset:19456
	ds_read_b128 v[202:205], v156 offset:20480
	ds_read_b128 v[206:209], v156 offset:21504
	ds_read_b128 v[210:213], v156 offset:22528
	ds_read_b128 v[214:217], v156 offset:23552
	global_load_lds_dwordx4 v132, s[22:23]
	s_add_i32 m0, s44, 0x2000
	s_add_u32 s44, s22, 0x80000
	s_addc_u32 s45, s23, 0
	s_add_i32 s46, s37, s27
	global_load_lds_dwordx4 v136, s[22:23]
	s_mov_b32 m0, s46
	global_load_lds_dwordx4 v132, s[44:45]
	s_add_i32 m0, s46, 0x2000
	s_nop 0
	global_load_lds_dwordx4 v136, s[44:45]
	s_mov_b32 m0, s19
	s_nop 0
	global_load_lds_dwordx4 v130, s[24:25]
	s_mov_b32 m0, s28
	s_nop 0
	global_load_lds_dwordx4 v134, s[24:25]
	s_waitcnt vmcnt(8)
	s_waitcnt lgkmcnt(0)
	s_barrier
	v_mfma_f32_16x16x32_bf16 v[62:65], v[146:149], v[186:189], v[62:65]
	v_mfma_f32_16x16x32_bf16 v[62:65], v[158:161], v[190:193], v[62:65]
	v_mfma_f32_16x16x32_bf16 v[58:61], v[162:165], v[186:189], v[58:61]
	v_mfma_f32_16x16x32_bf16 v[58:61], v[166:169], v[190:193], v[58:61]
	v_mfma_f32_16x16x32_bf16 v[46:49], v[146:149], v[194:197], v[46:49]
	v_mfma_f32_16x16x32_bf16 v[46:49], v[158:161], v[198:201], v[46:49]
	v_mfma_f32_16x16x32_bf16 v[42:45], v[162:165], v[194:197], v[42:45]
	v_mfma_f32_16x16x32_bf16 v[42:45], v[166:169], v[198:201], v[42:45]
	v_mfma_f32_16x16x32_bf16 v[30:33], v[146:149], v[202:205], v[30:33]
	v_mfma_f32_16x16x32_bf16 v[30:33], v[158:161], v[206:209], v[30:33]
	v_mfma_f32_16x16x32_bf16 v[26:29], v[162:165], v[202:205], v[26:29]
	v_mfma_f32_16x16x32_bf16 v[26:29], v[166:169], v[206:209], v[26:29]
	v_mfma_f32_16x16x32_bf16 v[14:17], v[146:149], v[210:213], v[14:17]
	v_mfma_f32_16x16x32_bf16 v[14:17], v[158:161], v[214:217], v[14:17]
	v_mfma_f32_16x16x32_bf16 v[10:13], v[162:165], v[210:213], v[10:13]
	v_mfma_f32_16x16x32_bf16 v[10:13], v[166:169], v[214:217], v[10:13]
	v_mfma_f32_16x16x32_bf16 v[54:57], v[170:173], v[186:189], v[54:57]
	v_mfma_f32_16x16x32_bf16 v[54:57], v[174:177], v[190:193], v[54:57]
	v_mfma_f32_16x16x32_bf16 v[50:53], v[178:181], v[186:189], v[50:53]
	v_mfma_f32_16x16x32_bf16 v[50:53], v[182:185], v[190:193], v[50:53]
	v_mfma_f32_16x16x32_bf16 v[38:41], v[170:173], v[194:197], v[38:41]
	v_mfma_f32_16x16x32_bf16 v[38:41], v[174:177], v[198:201], v[38:41]
	v_mfma_f32_16x16x32_bf16 v[34:37], v[178:181], v[194:197], v[34:37]
	v_mfma_f32_16x16x32_bf16 v[34:37], v[182:185], v[198:201], v[34:37]
	v_mfma_f32_16x16x32_bf16 v[22:25], v[170:173], v[202:205], v[22:25]
	v_mfma_f32_16x16x32_bf16 v[22:25], v[174:177], v[206:209], v[22:25]
	v_mfma_f32_16x16x32_bf16 v[18:21], v[178:181], v[202:205], v[18:21]
	v_mfma_f32_16x16x32_bf16 v[18:21], v[182:185], v[206:209], v[18:21]
	v_mfma_f32_16x16x32_bf16 v[6:9], v[170:173], v[210:213], v[6:9]
	v_mfma_f32_16x16x32_bf16 v[6:9], v[174:177], v[214:217], v[6:9]
	v_mfma_f32_16x16x32_bf16 v[2:5], v[178:181], v[210:213], v[2:5]
	v_mfma_f32_16x16x32_bf16 v[2:5], v[182:185], v[214:217], v[2:5]
	s_barrier
	s_add_i32 s44, 0, 0x18000
	s_add_i32 s45, 0, 0x1c000
	ds_read_b128 v[146:149], v246
	ds_read_b128 v[158:161], v246 offset:1024
	ds_read_b128 v[162:165], v246 offset:2048
	ds_read_b128 v[166:169], v246 offset:3072
	ds_read_b128 v[170:173], v247
	ds_read_b128 v[174:177], v247 offset:1024
	ds_read_b128 v[178:181], v247 offset:2048
	ds_read_b128 v[182:185], v247 offset:3072
	s_add_u32 s98, s24, 0x80
	s_addc_u32 s99, s25, 0
	s_add_u32 s24, s24, 0x80000
	s_addc_u32 s25, s25, 0
	s_mov_b32 m0, s29
	ds_read_b128 v[186:189], v156 offset:32768
	ds_read_b128 v[190:193], v156 offset:33792
	ds_read_b128 v[194:197], v156 offset:34816
	ds_read_b128 v[198:201], v156 offset:35840
	ds_read_b128 v[202:205], v156 offset:36864
	ds_read_b128 v[206:209], v156 offset:37888
	ds_read_b128 v[210:213], v156 offset:38912
	ds_read_b128 v[214:217], v156 offset:39936
	global_load_lds_dwordx4 v130, s[24:25]
	s_mov_b32 m0, s30
	s_nop 0
	global_load_lds_dwordx4 v134, s[24:25]
	s_waitcnt vmcnt(8)
	s_waitcnt lgkmcnt(0)
	s_barrier
	v_mfma_f32_16x16x32_bf16 v[126:129], v[146:149], v[186:189], v[126:129]
	v_mfma_f32_16x16x32_bf16 v[126:129], v[158:161], v[190:193], v[126:129]
	v_mfma_f32_16x16x32_bf16 v[122:125], v[162:165], v[186:189], v[122:125]
	v_mfma_f32_16x16x32_bf16 v[122:125], v[166:169], v[190:193], v[122:125]
	v_mfma_f32_16x16x32_bf16 v[110:113], v[146:149], v[194:197], v[110:113]
	v_mfma_f32_16x16x32_bf16 v[110:113], v[158:161], v[198:201], v[110:113]
	v_mfma_f32_16x16x32_bf16 v[106:109], v[162:165], v[194:197], v[106:109]
	v_mfma_f32_16x16x32_bf16 v[106:109], v[166:169], v[198:201], v[106:109]
	v_mfma_f32_16x16x32_bf16 v[94:97], v[146:149], v[202:205], v[94:97]
	v_mfma_f32_16x16x32_bf16 v[94:97], v[158:161], v[206:209], v[94:97]
	v_mfma_f32_16x16x32_bf16 v[90:93], v[162:165], v[202:205], v[90:93]
	v_mfma_f32_16x16x32_bf16 v[90:93], v[166:169], v[206:209], v[90:93]
	v_mfma_f32_16x16x32_bf16 v[78:81], v[146:149], v[210:213], v[78:81]
	v_mfma_f32_16x16x32_bf16 v[78:81], v[158:161], v[214:217], v[78:81]
	v_mfma_f32_16x16x32_bf16 v[74:77], v[162:165], v[210:213], v[74:77]
	v_mfma_f32_16x16x32_bf16 v[74:77], v[166:169], v[214:217], v[74:77]
	v_mfma_f32_16x16x32_bf16 v[118:121], v[170:173], v[186:189], v[118:121]
	v_mfma_f32_16x16x32_bf16 v[118:121], v[174:177], v[190:193], v[118:121]
	v_mfma_f32_16x16x32_bf16 v[114:117], v[178:181], v[186:189], v[114:117]
	v_mfma_f32_16x16x32_bf16 v[114:117], v[182:185], v[190:193], v[114:117]
	v_mfma_f32_16x16x32_bf16 v[102:105], v[170:173], v[194:197], v[102:105]
	v_mfma_f32_16x16x32_bf16 v[102:105], v[174:177], v[198:201], v[102:105]
	v_mfma_f32_16x16x32_bf16 v[98:101], v[178:181], v[194:197], v[98:101]
	v_mfma_f32_16x16x32_bf16 v[98:101], v[182:185], v[198:201], v[98:101]
	v_mfma_f32_16x16x32_bf16 v[86:89], v[170:173], v[202:205], v[86:89]
	v_mfma_f32_16x16x32_bf16 v[86:89], v[174:177], v[206:209], v[86:89]
	v_mfma_f32_16x16x32_bf16 v[82:85], v[178:181], v[202:205], v[82:85]
	v_mfma_f32_16x16x32_bf16 v[82:85], v[182:185], v[206:209], v[82:85]
	v_mfma_f32_16x16x32_bf16 v[70:73], v[170:173], v[210:213], v[70:73]
	v_mfma_f32_16x16x32_bf16 v[70:73], v[174:177], v[214:217], v[70:73]
	v_mfma_f32_16x16x32_bf16 v[66:69], v[178:181], v[210:213], v[66:69]
	v_mfma_f32_16x16x32_bf16 v[66:69], v[182:185], v[214:217], v[66:69]
	s_barrier
	s_add_i32 s24, s44, s27
	s_mov_b32 m0, s24
	ds_read_b128 v[186:189], v156 offset:49152
	ds_read_b128 v[190:193], v156 offset:50176
	ds_read_b128 v[194:197], v156 offset:51200
	ds_read_b128 v[198:201], v156 offset:52224
	ds_read_b128 v[202:205], v156 offset:53248
	ds_read_b128 v[206:209], v156 offset:54272
	ds_read_b128 v[210:213], v156 offset:55296
	ds_read_b128 v[214:217], v156 offset:56320
	s_add_u32 s22, s22, 0x80
	s_addc_u32 s23, s23, 0
	global_load_lds_dwordx4 v132, s[22:23]
	s_add_i32 m0, s24, 0x2000
	s_add_i32 s24, s45, s27
	global_load_lds_dwordx4 v136, s[22:23]
	s_add_u32 s22, s22, 0x80000
	s_addc_u32 s23, s23, 0
	s_mov_b32 m0, s24
	s_nop 0
	global_load_lds_dwordx4 v132, s[22:23]
	s_add_i32 m0, s24, 0x2000
	s_nop 0
	global_load_lds_dwordx4 v136, s[22:23]
	s_mov_b32 m0, s33
	s_nop 0
	global_load_lds_dwordx4 v130, s[98:99]
	s_mov_b32 m0, s34
	s_nop 0
	global_load_lds_dwordx4 v134, s[98:99]
	s_waitcnt vmcnt(8)
	s_waitcnt lgkmcnt(0)
	s_barrier
	v_mfma_f32_16x16x32_bf16 v[62:65], v[146:149], v[186:189], v[62:65]
	v_mfma_f32_16x16x32_bf16 v[62:65], v[158:161], v[190:193], v[62:65]
	v_mfma_f32_16x16x32_bf16 v[58:61], v[162:165], v[186:189], v[58:61]
	v_mfma_f32_16x16x32_bf16 v[58:61], v[166:169], v[190:193], v[58:61]
	v_mfma_f32_16x16x32_bf16 v[46:49], v[146:149], v[194:197], v[46:49]
	v_mfma_f32_16x16x32_bf16 v[46:49], v[158:161], v[198:201], v[46:49]
	v_mfma_f32_16x16x32_bf16 v[42:45], v[162:165], v[194:197], v[42:45]
	v_mfma_f32_16x16x32_bf16 v[42:45], v[166:169], v[198:201], v[42:45]
	v_mfma_f32_16x16x32_bf16 v[30:33], v[146:149], v[202:205], v[30:33]
	v_mfma_f32_16x16x32_bf16 v[30:33], v[158:161], v[206:209], v[30:33]
	v_mfma_f32_16x16x32_bf16 v[26:29], v[162:165], v[202:205], v[26:29]
	v_mfma_f32_16x16x32_bf16 v[26:29], v[166:169], v[206:209], v[26:29]
	v_mfma_f32_16x16x32_bf16 v[14:17], v[146:149], v[210:213], v[14:17]
	v_mfma_f32_16x16x32_bf16 v[14:17], v[158:161], v[214:217], v[14:17]
	v_mfma_f32_16x16x32_bf16 v[10:13], v[162:165], v[210:213], v[10:13]
	v_mfma_f32_16x16x32_bf16 v[10:13], v[166:169], v[214:217], v[10:13]
	v_mfma_f32_16x16x32_bf16 v[54:57], v[170:173], v[186:189], v[54:57]
	v_mfma_f32_16x16x32_bf16 v[54:57], v[174:177], v[190:193], v[54:57]
	v_mfma_f32_16x16x32_bf16 v[50:53], v[178:181], v[186:189], v[50:53]
	v_mfma_f32_16x16x32_bf16 v[50:53], v[182:185], v[190:193], v[50:53]
	v_mfma_f32_16x16x32_bf16 v[38:41], v[170:173], v[194:197], v[38:41]
	v_mfma_f32_16x16x32_bf16 v[38:41], v[174:177], v[198:201], v[38:41]
	v_mfma_f32_16x16x32_bf16 v[34:37], v[178:181], v[194:197], v[34:37]
	v_mfma_f32_16x16x32_bf16 v[34:37], v[182:185], v[198:201], v[34:37]
	v_mfma_f32_16x16x32_bf16 v[22:25], v[170:173], v[202:205], v[22:25]
	v_mfma_f32_16x16x32_bf16 v[22:25], v[174:177], v[206:209], v[22:25]
	v_mfma_f32_16x16x32_bf16 v[18:21], v[178:181], v[202:205], v[18:21]
	v_mfma_f32_16x16x32_bf16 v[18:21], v[182:185], v[206:209], v[18:21]
	v_mfma_f32_16x16x32_bf16 v[6:9], v[170:173], v[210:213], v[6:9]
	v_mfma_f32_16x16x32_bf16 v[6:9], v[174:177], v[214:217], v[6:9]
	v_mfma_f32_16x16x32_bf16 v[2:5], v[178:181], v[210:213], v[2:5]
	v_mfma_f32_16x16x32_bf16 v[2:5], v[182:185], v[214:217], v[2:5]
	s_barrier
	s_add_i32 s43, s43, 2
	s_add_u32 s20, s20, 0x100
	s_addc_u32 s21, s21, 0
	s_add_u32 s41, s41, 0x100
	s_addc_u32 s42, s42, 0
	s_cmp_gt_u32 s43, 29
	s_cbranch_scc0 .LBB0_863
	s_setprio 0
	s_and_b64 vcc, exec, s[8:9]
	s_cbranch_vccz .LBB0_866
	s_barrier

.LBB0_940:
	s_ashr_i32 s21, s20, 31
	s_lshl_b64 s[22:23], s[20:21], 21
	s_add_u32 s22, s0, s22
	s_addc_u32 s23, s1, s23
	s_and_b64 s[24:25], s[4:5], exec
	s_cselect_b32 s21, s23, s29
	s_cselect_b32 s27, s22, s28
	s_ashr_i32 s19, s18, 31
	s_lshl_b64 s[24:25], s[18:19], 21
	v_readlane_b32 s34, v245, 18
	v_readlane_b32 s35, v245, 19
	s_add_u32 s24, s34, s24
	s_addc_u32 s25, s35, s25
	s_and_b64 s[34:35], s[4:5], exec
	s_cselect_b32 s19, s25, s31
	s_cselect_b32 s48, s24, s30
	s_add_u32 s28, s28, 0x100080
	s_addc_u32 s29, s29, 0
	s_add_u32 s49, s30, 0x100
	v_mov_b32_e32 v2, 0
	s_addc_u32 s50, s31, 0
	s_mov_b32 s51, -2
	s_waitcnt lgkmcnt(0)
	v_mov_b64_e32 v[2:3], 0
	v_mov_b64_e32 v[4:5], 0
	v_mov_b64_e32 v[6:7], 0
	v_mov_b64_e32 v[8:9], 0
	v_mov_b64_e32 v[10:11], 0
	v_mov_b64_e32 v[12:13], 0
	v_mov_b64_e32 v[14:15], 0
	v_mov_b64_e32 v[16:17], 0
	v_mov_b64_e32 v[18:19], 0
	v_mov_b64_e32 v[20:21], 0
	v_mov_b64_e32 v[22:23], 0
	v_mov_b64_e32 v[24:25], 0
	v_mov_b64_e32 v[26:27], 0
	v_mov_b64_e32 v[28:29], 0
	v_mov_b64_e32 v[30:31], 0
	v_mov_b64_e32 v[32:33], 0
	v_mov_b64_e32 v[34:35], 0
	v_mov_b64_e32 v[36:37], 0
	v_mov_b64_e32 v[38:39], 0
	v_mov_b64_e32 v[40:41], 0
	v_mov_b64_e32 v[42:43], 0
	v_mov_b64_e32 v[44:45], 0
	v_mov_b64_e32 v[46:47], 0
	v_mov_b64_e32 v[48:49], 0
	v_mov_b64_e32 v[50:51], 0
	v_mov_b64_e32 v[52:53], 0
	v_mov_b64_e32 v[54:55], 0
	v_mov_b64_e32 v[56:57], 0
	v_mov_b64_e32 v[58:59], 0
	v_mov_b64_e32 v[60:61], 0
	v_mov_b64_e32 v[62:63], 0
	v_mov_b64_e32 v[64:65], 0
	v_mov_b64_e32 v[66:67], 0
	v_mov_b64_e32 v[68:69], 0
	v_mov_b64_e32 v[70:71], 0
	v_mov_b64_e32 v[72:73], 0
	v_mov_b64_e32 v[82:83], 0
	v_mov_b64_e32 v[84:85], 0
	v_mov_b64_e32 v[86:87], 0
	v_mov_b64_e32 v[88:89], 0
	s_waitcnt vmcnt(0)
	v_mov_b64_e32 v[74:75], 0
	v_mov_b64_e32 v[76:77], 0
	v_mov_b64_e32 v[78:79], 0
	v_mov_b64_e32 v[80:81], 0
	v_mov_b64_e32 v[98:99], 0
	v_mov_b64_e32 v[100:101], 0
	v_mov_b64_e32 v[106:107], 0
	v_mov_b64_e32 v[108:109], 0
	v_mov_b64_e32 v[114:115], 0
	v_mov_b64_e32 v[116:117], 0
	v_mov_b64_e32 v[118:119], 0
	v_mov_b64_e32 v[120:121], 0
	v_mov_b64_e32 v[122:123], 0
	v_mov_b64_e32 v[124:125], 0
	v_mov_b64_e32 v[126:127], 0
	v_mov_b64_e32 v[128:129], 0
	v_mov_b64_e32 v[130:131], 0
	v_mov_b64_e32 v[132:133], 0
	v_mov_b64_e32 v[134:135], 0
	v_mov_b64_e32 v[136:137], 0
	v_mov_b64_e32 v[138:139], 0
	v_mov_b64_e32 v[140:141], 0
	v_mov_b64_e32 v[142:143], 0
	v_mov_b64_e32 v[144:145], 0
	v_add_u32_e32 v246, 0x18000, v186
	v_add_u32_e32 v247, 0x1c000, v186
	v_cmp_gt_u32_e32 vcc, 0x100, v0
	s_cbranch_vccnz .Lgprio_941
	s_setprio 1
.Lgprio_941:
.LBB0_941:
	ds_read_b128 v[90:93], v188
	ds_read_b128 v[94:97], v188 offset:1024
	ds_read_b128 v[102:105], v188 offset:2048
	ds_read_b128 v[110:113], v188 offset:3072
	ds_read_b128 v[146:149], v189
	ds_read_b128 v[150:153], v189 offset:1024
	ds_read_b128 v[154:157], v189 offset:2048
	ds_read_b128 v[158:161], v189 offset:3072
	s_add_u32 s30, s28, 0xfff00080
	s_addc_u32 s31, s29, -1
	s_cmp_eq_u32 s51, 60
	s_cselect_b32 s35, s21, s31
	s_cselect_b32 s34, s27, s30
	s_cselect_b32 s31, s19, s50
	s_cselect_b32 s30, s48, s49
	s_add_i32 m0, s36, 0xc000
	ds_read_b128 v[178:181], v190
	ds_read_b128 v[182:185], v190 offset:1024
	ds_read_b128 v[192:195], v190 offset:2048
	ds_read_b128 v[196:199], v190 offset:3072
	ds_read_b128 v[200:203], v190 offset:4096
	ds_read_b128 v[204:207], v190 offset:5120
	ds_read_b128 v[208:211], v190 offset:6144
	ds_read_b128 v[212:215], v190 offset:7168
	global_load_lds_dwordx4 v170, s[28:29]
	s_add_i32 m0, s36, 0xe000
	s_nop 0
	global_load_lds_dwordx4 v172, s[28:29]
	s_waitcnt vmcnt(8)
	s_waitcnt lgkmcnt(0)
	s_barrier
	v_mfma_f32_16x16x32_bf16 v[142:145], v[90:93], v[178:181], v[142:145]
	v_mfma_f32_16x16x32_bf16 v[142:145], v[94:97], v[182:185], v[142:145]
	v_mfma_f32_16x16x32_bf16 v[138:141], v[102:105], v[178:181], v[138:141]
	v_mfma_f32_16x16x32_bf16 v[138:141], v[110:113], v[182:185], v[138:141]
	v_mfma_f32_16x16x32_bf16 v[126:129], v[90:93], v[192:195], v[126:129]
	v_mfma_f32_16x16x32_bf16 v[126:129], v[94:97], v[196:199], v[126:129]
	v_mfma_f32_16x16x32_bf16 v[122:125], v[102:105], v[192:195], v[122:125]
	v_mfma_f32_16x16x32_bf16 v[122:125], v[110:113], v[196:199], v[122:125]
	v_mfma_f32_16x16x32_bf16 v[106:109], v[90:93], v[200:203], v[106:109]
	v_mfma_f32_16x16x32_bf16 v[106:109], v[94:97], v[204:207], v[106:109]
	v_mfma_f32_16x16x32_bf16 v[98:101], v[102:105], v[200:203], v[98:101]
	v_mfma_f32_16x16x32_bf16 v[98:101], v[110:113], v[204:207], v[98:101]
	v_mfma_f32_16x16x32_bf16 v[78:81], v[90:93], v[208:211], v[78:81]
	v_mfma_f32_16x16x32_bf16 v[78:81], v[94:97], v[212:215], v[78:81]
	v_mfma_f32_16x16x32_bf16 v[74:77], v[102:105], v[208:211], v[74:77]
	v_mfma_f32_16x16x32_bf16 v[74:77], v[110:113], v[212:215], v[74:77]
	v_mfma_f32_16x16x32_bf16 v[134:137], v[146:149], v[178:181], v[134:137]
	v_mfma_f32_16x16x32_bf16 v[134:137], v[150:153], v[182:185], v[134:137]
	v_mfma_f32_16x16x32_bf16 v[130:133], v[154:157], v[178:181], v[130:133]
	v_mfma_f32_16x16x32_bf16 v[130:133], v[158:161], v[182:185], v[130:133]
	v_mfma_f32_16x16x32_bf16 v[118:121], v[146:149], v[192:195], v[118:121]
	v_mfma_f32_16x16x32_bf16 v[118:121], v[150:153], v[196:199], v[118:121]
	v_mfma_f32_16x16x32_bf16 v[114:117], v[154:157], v[192:195], v[114:117]
	v_mfma_f32_16x16x32_bf16 v[114:117], v[158:161], v[196:199], v[114:117]
	v_mfma_f32_16x16x32_bf16 v[86:89], v[146:149], v[200:203], v[86:89]
	v_mfma_f32_16x16x32_bf16 v[86:89], v[150:153], v[204:207], v[86:89]
	v_mfma_f32_16x16x32_bf16 v[82:85], v[154:157], v[200:203], v[82:85]
	v_mfma_f32_16x16x32_bf16 v[82:85], v[158:161], v[204:207], v[82:85]
	v_mfma_f32_16x16x32_bf16 v[70:73], v[146:149], v[208:211], v[70:73]
	v_mfma_f32_16x16x32_bf16 v[70:73], v[150:153], v[212:215], v[70:73]
	v_mfma_f32_16x16x32_bf16 v[66:69], v[154:157], v[208:211], v[66:69]
	v_mfma_f32_16x16x32_bf16 v[66:69], v[158:161], v[212:215], v[66:69]
	s_barrier
	s_add_i32 s52, s45, s33
	s_mov_b32 m0, s52
	ds_read_b128 v[178:181], v190 offset:16384
	ds_read_b128 v[182:185], v190 offset:17408
	ds_read_b128 v[192:195], v190 offset:18432
	ds_read_b128 v[196:199], v190 offset:19456
	ds_read_b128 v[200:203], v190 offset:20480
	ds_read_b128 v[204:207], v190 offset:21504
	ds_read_b128 v[208:211], v190 offset:22528
	ds_read_b128 v[212:215], v190 offset:23552
	global_load_lds_dwordx4 v164, s[30:31]
	s_add_i32 m0, s52, 0x2000
	s_add_u32 s52, s30, 0x100000
	s_addc_u32 s53, s31, 0
	s_add_i32 s54, s46, s33
	global_load_lds_dwordx4 v168, s[30:31]
	s_mov_b32 m0, s54
	global_load_lds_dwordx4 v164, s[52:53]
	s_add_i32 m0, s54, 0x2000
	s_nop 0
	global_load_lds_dwordx4 v168, s[52:53]
	s_mov_b32 m0, s36
	s_nop 0
	global_load_lds_dwordx4 v162, s[34:35]
	s_mov_b32 m0, s37
	s_nop 0
	global_load_lds_dwordx4 v166, s[34:35]
	s_waitcnt vmcnt(8)
	s_waitcnt lgkmcnt(0)
	s_barrier
	v_mfma_f32_16x16x32_bf16 v[62:65], v[90:93], v[178:181], v[62:65]
	v_mfma_f32_16x16x32_bf16 v[62:65], v[94:97], v[182:185], v[62:65]
	v_mfma_f32_16x16x32_bf16 v[58:61], v[102:105], v[178:181], v[58:61]
	v_mfma_f32_16x16x32_bf16 v[58:61], v[110:113], v[182:185], v[58:61]
	v_mfma_f32_16x16x32_bf16 v[46:49], v[90:93], v[192:195], v[46:49]
	v_mfma_f32_16x16x32_bf16 v[46:49], v[94:97], v[196:199], v[46:49]
	v_mfma_f32_16x16x32_bf16 v[42:45], v[102:105], v[192:195], v[42:45]
	v_mfma_f32_16x16x32_bf16 v[42:45], v[110:113], v[196:199], v[42:45]
	v_mfma_f32_16x16x32_bf16 v[30:33], v[90:93], v[200:203], v[30:33]
	v_mfma_f32_16x16x32_bf16 v[30:33], v[94:97], v[204:207], v[30:33]
	v_mfma_f32_16x16x32_bf16 v[26:29], v[102:105], v[200:203], v[26:29]
	v_mfma_f32_16x16x32_bf16 v[26:29], v[110:113], v[204:207], v[26:29]
	v_mfma_f32_16x16x32_bf16 v[14:17], v[90:93], v[208:211], v[14:17]
	v_mfma_f32_16x16x32_bf16 v[14:17], v[94:97], v[212:215], v[14:17]
	v_mfma_f32_16x16x32_bf16 v[10:13], v[102:105], v[208:211], v[10:13]
	v_mfma_f32_16x16x32_bf16 v[10:13], v[110:113], v[212:215], v[10:13]
	v_mfma_f32_16x16x32_bf16 v[54:57], v[146:149], v[178:181], v[54:57]
	v_mfma_f32_16x16x32_bf16 v[54:57], v[150:153], v[182:185], v[54:57]
	v_mfma_f32_16x16x32_bf16 v[50:53], v[154:157], v[178:181], v[50:53]
	v_mfma_f32_16x16x32_bf16 v[50:53], v[158:161], v[182:185], v[50:53]
	v_mfma_f32_16x16x32_bf16 v[38:41], v[146:149], v[192:195], v[38:41]
	v_mfma_f32_16x16x32_bf16 v[38:41], v[150:153], v[196:199], v[38:41]
	v_mfma_f32_16x16x32_bf16 v[34:37], v[154:157], v[192:195], v[34:37]
	v_mfma_f32_16x16x32_bf16 v[34:37], v[158:161], v[196:199], v[34:37]
	v_mfma_f32_16x16x32_bf16 v[22:25], v[146:149], v[200:203], v[22:25]
	v_mfma_f32_16x16x32_bf16 v[22:25], v[150:153], v[204:207], v[22:25]
	v_mfma_f32_16x16x32_bf16 v[18:21], v[154:157], v[200:203], v[18:21]
	v_mfma_f32_16x16x32_bf16 v[18:21], v[158:161], v[204:207], v[18:21]
	v_mfma_f32_16x16x32_bf16 v[6:9], v[146:149], v[208:211], v[6:9]
	v_mfma_f32_16x16x32_bf16 v[6:9], v[150:153], v[212:215], v[6:9]
	v_mfma_f32_16x16x32_bf16 v[2:5], v[154:157], v[208:211], v[2:5]
	v_mfma_f32_16x16x32_bf16 v[2:5], v[158:161], v[212:215], v[2:5]
	s_barrier
	s_add_i32 s52, 0, 0x18000
	s_add_i32 s53, 0, 0x1c000
	ds_read_b128 v[90:93], v246
	ds_read_b128 v[94:97], v246 offset:1024
	ds_read_b128 v[102:105], v246 offset:2048
	ds_read_b128 v[110:113], v246 offset:3072
	ds_read_b128 v[146:149], v247
	ds_read_b128 v[150:153], v247 offset:1024
	ds_read_b128 v[154:157], v247 offset:2048
	ds_read_b128 v[158:161], v247 offset:3072
	s_add_u32 s98, s34, 0x80
	s_addc_u32 s99, s35, 0
	s_add_u32 s34, s34, 0x100000
	s_addc_u32 s35, s35, 0
	s_mov_b32 m0, s38
	ds_read_b128 v[178:181], v190 offset:32768
	ds_read_b128 v[182:185], v190 offset:33792
	ds_read_b128 v[192:195], v190 offset:34816
	ds_read_b128 v[196:199], v190 offset:35840
	ds_read_b128 v[200:203], v190 offset:36864
	ds_read_b128 v[204:207], v190 offset:37888
	ds_read_b128 v[208:211], v190 offset:38912
	ds_read_b128 v[212:215], v190 offset:39936
	global_load_lds_dwordx4 v162, s[34:35]
	s_mov_b32 m0, s39
	s_nop 0
	global_load_lds_dwordx4 v166, s[34:35]
	s_waitcnt vmcnt(8)
	s_waitcnt lgkmcnt(0)
	s_barrier
	v_mfma_f32_16x16x32_bf16 v[142:145], v[90:93], v[178:181], v[142:145]
	v_mfma_f32_16x16x32_bf16 v[142:145], v[94:97], v[182:185], v[142:145]
	v_mfma_f32_16x16x32_bf16 v[138:141], v[102:105], v[178:181], v[138:141]
	v_mfma_f32_16x16x32_bf16 v[138:141], v[110:113], v[182:185], v[138:141]
	v_mfma_f32_16x16x32_bf16 v[126:129], v[90:93], v[192:195], v[126:129]
	v_mfma_f32_16x16x32_bf16 v[126:129], v[94:97], v[196:199], v[126:129]
	v_mfma_f32_16x16x32_bf16 v[122:125], v[102:105], v[192:195], v[122:125]
	v_mfma_f32_16x16x32_bf16 v[122:125], v[110:113], v[196:199], v[122:125]
	v_mfma_f32_16x16x32_bf16 v[106:109], v[90:93], v[200:203], v[106:109]
	v_mfma_f32_16x16x32_bf16 v[106:109], v[94:97], v[204:207], v[106:109]
	v_mfma_f32_16x16x32_bf16 v[98:101], v[102:105], v[200:203], v[98:101]
	v_mfma_f32_16x16x32_bf16 v[98:101], v[110:113], v[204:207], v[98:101]
	v_mfma_f32_16x16x32_bf16 v[78:81], v[90:93], v[208:211], v[78:81]
	v_mfma_f32_16x16x32_bf16 v[78:81], v[94:97], v[212:215], v[78:81]
	v_mfma_f32_16x16x32_bf16 v[74:77], v[102:105], v[208:211], v[74:77]
	v_mfma_f32_16x16x32_bf16 v[74:77], v[110:113], v[212:215], v[74:77]
	v_mfma_f32_16x16x32_bf16 v[134:137], v[146:149], v[178:181], v[134:137]
	v_mfma_f32_16x16x32_bf16 v[134:137], v[150:153], v[182:185], v[134:137]
	v_mfma_f32_16x16x32_bf16 v[130:133], v[154:157], v[178:181], v[130:133]
	v_mfma_f32_16x16x32_bf16 v[130:133], v[158:161], v[182:185], v[130:133]
	v_mfma_f32_16x16x32_bf16 v[118:121], v[146:149], v[192:195], v[118:121]
	v_mfma_f32_16x16x32_bf16 v[118:121], v[150:153], v[196:199], v[118:121]
	v_mfma_f32_16x16x32_bf16 v[114:117], v[154:157], v[192:195], v[114:117]
	v_mfma_f32_16x16x32_bf16 v[114:117], v[158:161], v[196:199], v[114:117]
	v_mfma_f32_16x16x32_bf16 v[86:89], v[146:149], v[200:203], v[86:89]
	v_mfma_f32_16x16x32_bf16 v[86:89], v[150:153], v[204:207], v[86:89]
	v_mfma_f32_16x16x32_bf16 v[82:85], v[154:157], v[200:203], v[82:85]
	v_mfma_f32_16x16x32_bf16 v[82:85], v[158:161], v[204:207], v[82:85]
	v_mfma_f32_16x16x32_bf16 v[70:73], v[146:149], v[208:211], v[70:73]
	v_mfma_f32_16x16x32_bf16 v[70:73], v[150:153], v[212:215], v[70:73]
	v_mfma_f32_16x16x32_bf16 v[66:69], v[154:157], v[208:211], v[66:69]
	v_mfma_f32_16x16x32_bf16 v[66:69], v[158:161], v[212:215], v[66:69]
	s_barrier
	s_add_i32 s34, s52, s33
	s_mov_b32 m0, s34
	ds_read_b128 v[178:181], v190 offset:49152
	ds_read_b128 v[182:185], v190 offset:50176
	ds_read_b128 v[192:195], v190 offset:51200
	ds_read_b128 v[196:199], v190 offset:52224
	ds_read_b128 v[200:203], v190 offset:53248
	ds_read_b128 v[204:207], v190 offset:54272
	ds_read_b128 v[208:211], v190 offset:55296
	ds_read_b128 v[212:215], v190 offset:56320
	s_add_u32 s30, s30, 0x80
	s_addc_u32 s31, s31, 0
	global_load_lds_dwordx4 v164, s[30:31]
	s_add_i32 m0, s34, 0x2000
	s_add_i32 s34, s53, s33
	global_load_lds_dwordx4 v168, s[30:31]
	s_add_u32 s30, s30, 0x100000
	s_addc_u32 s31, s31, 0
	s_mov_b32 m0, s34
	s_nop 0
	global_load_lds_dwordx4 v164, s[30:31]
	s_add_i32 m0, s34, 0x2000
	s_nop 0
	global_load_lds_dwordx4 v168, s[30:31]
	s_mov_b32 m0, s43
	s_nop 0
	global_load_lds_dwordx4 v162, s[98:99]
	s_mov_b32 m0, s44
	s_nop 0
	global_load_lds_dwordx4 v166, s[98:99]
	s_waitcnt vmcnt(8)
	s_waitcnt lgkmcnt(0)
	s_barrier
	v_mfma_f32_16x16x32_bf16 v[62:65], v[90:93], v[178:181], v[62:65]
	v_mfma_f32_16x16x32_bf16 v[62:65], v[94:97], v[182:185], v[62:65]
	v_mfma_f32_16x16x32_bf16 v[58:61], v[102:105], v[178:181], v[58:61]
	v_mfma_f32_16x16x32_bf16 v[58:61], v[110:113], v[182:185], v[58:61]
	v_mfma_f32_16x16x32_bf16 v[46:49], v[90:93], v[192:195], v[46:49]
	v_mfma_f32_16x16x32_bf16 v[46:49], v[94:97], v[196:199], v[46:49]
	v_mfma_f32_16x16x32_bf16 v[42:45], v[102:105], v[192:195], v[42:45]
	v_mfma_f32_16x16x32_bf16 v[42:45], v[110:113], v[196:199], v[42:45]
	v_mfma_f32_16x16x32_bf16 v[30:33], v[90:93], v[200:203], v[30:33]
	v_mfma_f32_16x16x32_bf16 v[30:33], v[94:97], v[204:207], v[30:33]
	v_mfma_f32_16x16x32_bf16 v[26:29], v[102:105], v[200:203], v[26:29]
	v_mfma_f32_16x16x32_bf16 v[26:29], v[110:113], v[204:207], v[26:29]
	v_mfma_f32_16x16x32_bf16 v[14:17], v[90:93], v[208:211], v[14:17]
	v_mfma_f32_16x16x32_bf16 v[14:17], v[94:97], v[212:215], v[14:17]
	v_mfma_f32_16x16x32_bf16 v[10:13], v[102:105], v[208:211], v[10:13]
	v_mfma_f32_16x16x32_bf16 v[10:13], v[110:113], v[212:215], v[10:13]
	v_mfma_f32_16x16x32_bf16 v[54:57], v[146:149], v[178:181], v[54:57]
	v_mfma_f32_16x16x32_bf16 v[54:57], v[150:153], v[182:185], v[54:57]
	v_mfma_f32_16x16x32_bf16 v[50:53], v[154:157], v[178:181], v[50:53]
	v_mfma_f32_16x16x32_bf16 v[50:53], v[158:161], v[182:185], v[50:53]
	v_mfma_f32_16x16x32_bf16 v[38:41], v[146:149], v[192:195], v[38:41]
	v_mfma_f32_16x16x32_bf16 v[38:41], v[150:153], v[196:199], v[38:41]
	v_mfma_f32_16x16x32_bf16 v[34:37], v[154:157], v[192:195], v[34:37]
	v_mfma_f32_16x16x32_bf16 v[34:37], v[158:161], v[196:199], v[34:37]
	v_mfma_f32_16x16x32_bf16 v[22:25], v[146:149], v[200:203], v[22:25]
	v_mfma_f32_16x16x32_bf16 v[22:25], v[150:153], v[204:207], v[22:25]
	v_mfma_f32_16x16x32_bf16 v[18:21], v[154:157], v[200:203], v[18:21]
	v_mfma_f32_16x16x32_bf16 v[18:21], v[158:161], v[204:207], v[18:21]
	v_mfma_f32_16x16x32_bf16 v[6:9], v[146:149], v[208:211], v[6:9]
	v_mfma_f32_16x16x32_bf16 v[6:9], v[150:153], v[212:215], v[6:9]
	v_mfma_f32_16x16x32_bf16 v[2:5], v[154:157], v[208:211], v[2:5]
	v_mfma_f32_16x16x32_bf16 v[2:5], v[158:161], v[212:215], v[2:5]
	s_barrier
	s_add_i32 s51, s51, 2
	s_add_u32 s28, s28, 0x100
	s_addc_u32 s29, s29, 0
	s_add_u32 s49, s49, 0x100
	s_addc_u32 s50, s50, 0
	s_cmp_gt_u32 s51, 61
	s_cbranch_scc0 .LBB0_941
	s_setprio 0
	s_and_b64 vcc, exec, s[16:17]
	s_cbranch_vccz .LBB0_944
	s_barrier

.LBB0_1152:
	s_xor_b64 s[48:49], s[54:55], -1
	s_add_u32 s33, s56, 0x100
	s_addc_u32 s72, s57, 0
	s_ashr_i32 s45, s44, 31
	s_lshl_b64 s[50:51], s[44:45], 21
	s_add_u32 s50, s70, s50
	s_addc_u32 s51, s71, s51
	s_and_b64 s[52:53], s[54:55], exec
	s_cselect_b32 s29, s51, s47
	s_cselect_b32 s45, s50, s46
	s_ashr_i32 s43, s42, 31
	s_lshl_b64 s[52:53], s[42:43], 21
	v_readlane_b32 s20, v244, 4
	v_readlane_b32 s21, v244, 5
	s_add_u32 s52, s20, s52
	s_addc_u32 s53, s21, s53
	s_and_b64 s[58:59], s[54:55], exec
	s_cselect_b32 s43, s53, s57
	s_cselect_b32 s73, s52, s56
	v_lshl_add_u64 v[130:131], s[46:47], 0, v[196:197]
	v_lshl_add_u64 v[132:133], s[46:47], 0, v[198:199]
	s_mov_b32 s83, -2
	v_add_u32_e32 v246, 0x18000, v187
	v_add_u32_e32 v247, 0x1c000, v187
	v_cmp_gt_u32_e32 vcc, 0x100, v0
	s_cbranch_vccnz .Lgprio_1153
	s_setprio 1
.Lgprio_1153:
.LBB0_1153:
	v_add_u32_e32 v146, s78, v187
	v_add_u32_e32 v162, s79, v187
	s_add_u32 s98, s46, s10
	s_addc_u32 s99, s47, s11
	s_add_u32 s98, s98, 0x100080
	s_addc_u32 s99, s99, 0
	s_add_u32 s56, s46, s10
	ds_read_b128 v[134:137], v146
	ds_read_b128 v[138:141], v146 offset:1024
	ds_read_b128 v[142:145], v146 offset:2048
	ds_read_b128 v[146:149], v146 offset:3072
	ds_read_b128 v[150:153], v162
	ds_read_b128 v[154:157], v162 offset:1024
	ds_read_b128 v[158:161], v162 offset:2048
	ds_read_b128 v[162:165], v162 offset:3072
	s_addc_u32 s57, s47, s11
	s_add_u32 s56, s56, 0x100
	s_addc_u32 s57, s57, 0
	s_add_u32 s84, s33, s10
	s_addc_u32 s85, s72, s11
	s_cmpk_eq_i32 s10, 0x1f00
	s_cselect_b32 s59, s29, s57
	s_cselect_b32 s58, s45, s56
	s_cselect_b32 s57, s43, s85
	s_cselect_b32 s56, s73, s84
	s_add_i32 m0, s64, 0xc000
	ds_read_b128 v[166:169], v230
	ds_read_b128 v[170:173], v230 offset:1024
	ds_read_b128 v[174:177], v230 offset:2048
	ds_read_b128 v[202:205], v230 offset:3072
	ds_read_b128 v[206:209], v230 offset:4096
	ds_read_b128 v[210:213], v230 offset:5120
	ds_read_b128 v[214:217], v230 offset:6144
	ds_read_b128 v[218:221], v230 offset:7168
	global_load_lds_dwordx4 v178, s[98:99]
	s_add_i32 m0, s64, 0xe000
	s_nop 0
	global_load_lds_dwordx4 v182, s[98:99]
	s_waitcnt vmcnt(8)
	s_waitcnt lgkmcnt(0)
	s_barrier
	v_mfma_f32_16x16x32_bf16 v[2:5], v[134:137], v[166:169], v[2:5]
	v_mfma_f32_16x16x32_bf16 v[2:5], v[138:141], v[170:173], v[2:5]
	v_mfma_f32_16x16x32_bf16 v[126:129], v[142:145], v[166:169], v[126:129]
	v_mfma_f32_16x16x32_bf16 v[126:129], v[146:149], v[170:173], v[126:129]
	v_mfma_f32_16x16x32_bf16 v[122:125], v[134:137], v[174:177], v[122:125]
	v_mfma_f32_16x16x32_bf16 v[122:125], v[138:141], v[202:205], v[122:125]
	v_mfma_f32_16x16x32_bf16 v[118:121], v[142:145], v[174:177], v[118:121]
	v_mfma_f32_16x16x32_bf16 v[118:121], v[146:149], v[202:205], v[118:121]
	v_mfma_f32_16x16x32_bf16 v[114:117], v[134:137], v[206:209], v[114:117]
	v_mfma_f32_16x16x32_bf16 v[114:117], v[138:141], v[210:213], v[114:117]
	v_mfma_f32_16x16x32_bf16 v[110:113], v[142:145], v[206:209], v[110:113]
	v_mfma_f32_16x16x32_bf16 v[110:113], v[146:149], v[210:213], v[110:113]
	v_mfma_f32_16x16x32_bf16 v[106:109], v[134:137], v[214:217], v[106:109]
	v_mfma_f32_16x16x32_bf16 v[106:109], v[138:141], v[218:221], v[106:109]
	v_mfma_f32_16x16x32_bf16 v[102:105], v[142:145], v[214:217], v[102:105]
	v_mfma_f32_16x16x32_bf16 v[102:105], v[146:149], v[218:221], v[102:105]
	v_mfma_f32_16x16x32_bf16 v[98:101], v[150:153], v[166:169], v[98:101]
	v_mfma_f32_16x16x32_bf16 v[98:101], v[154:157], v[170:173], v[98:101]
	v_mfma_f32_16x16x32_bf16 v[94:97], v[158:161], v[166:169], v[94:97]
	v_mfma_f32_16x16x32_bf16 v[94:97], v[162:165], v[170:173], v[94:97]
	v_mfma_f32_16x16x32_bf16 v[90:93], v[150:153], v[174:177], v[90:93]
	v_mfma_f32_16x16x32_bf16 v[90:93], v[154:157], v[202:205], v[90:93]
	v_mfma_f32_16x16x32_bf16 v[86:89], v[158:161], v[174:177], v[86:89]
	v_mfma_f32_16x16x32_bf16 v[86:89], v[162:165], v[202:205], v[86:89]
	v_mfma_f32_16x16x32_bf16 v[82:85], v[150:153], v[206:209], v[82:85]
	v_mfma_f32_16x16x32_bf16 v[82:85], v[154:157], v[210:213], v[82:85]
	v_mfma_f32_16x16x32_bf16 v[78:81], v[158:161], v[206:209], v[78:81]
	v_mfma_f32_16x16x32_bf16 v[78:81], v[162:165], v[210:213], v[78:81]
	v_mfma_f32_16x16x32_bf16 v[74:77], v[150:153], v[214:217], v[74:77]
	v_mfma_f32_16x16x32_bf16 v[74:77], v[154:157], v[218:221], v[74:77]
	v_mfma_f32_16x16x32_bf16 v[70:73], v[158:161], v[214:217], v[70:73]
	v_mfma_f32_16x16x32_bf16 v[70:73], v[162:165], v[218:221], v[70:73]
	s_barrier
	s_add_i32 s84, s78, s63
	s_mov_b32 m0, s84
	ds_read_b128 v[166:169], v230 offset:16384
	ds_read_b128 v[170:173], v230 offset:17408
	ds_read_b128 v[174:177], v230 offset:18432
	ds_read_b128 v[202:205], v230 offset:19456
	ds_read_b128 v[206:209], v230 offset:20480
	ds_read_b128 v[210:213], v230 offset:21504
	ds_read_b128 v[214:217], v230 offset:22528
	ds_read_b128 v[218:221], v230 offset:23552
	global_load_lds_dwordx4 v180, s[56:57]
	s_add_i32 m0, s84, 0x2000
	s_add_u32 s84, s56, 0x100000
	s_addc_u32 s85, s57, 0
	s_add_i32 s86, s79, s63
	global_load_lds_dwordx4 v184, s[56:57]
	s_mov_b32 m0, s86
	s_nop 0
	global_load_lds_dwordx4 v180, s[84:85]
	s_add_i32 m0, s86, 0x2000
	s_nop 0
	global_load_lds_dwordx4 v184, s[84:85]
	s_mov_b32 m0, s64
	s_nop 0
	global_load_lds_dwordx4 v178, s[58:59]
	s_mov_b32 m0, s65
	s_nop 0
	global_load_lds_dwordx4 v182, s[58:59]
	s_waitcnt vmcnt(8)
	s_waitcnt lgkmcnt(0)
	s_barrier
	v_mfma_f32_16x16x32_bf16 v[66:69], v[134:137], v[166:169], v[66:69]
	v_mfma_f32_16x16x32_bf16 v[66:69], v[138:141], v[170:173], v[66:69]
	v_mfma_f32_16x16x32_bf16 v[62:65], v[142:145], v[166:169], v[62:65]
	v_mfma_f32_16x16x32_bf16 v[62:65], v[146:149], v[170:173], v[62:65]
	v_mfma_f32_16x16x32_bf16 v[58:61], v[134:137], v[174:177], v[58:61]
	v_mfma_f32_16x16x32_bf16 v[58:61], v[138:141], v[202:205], v[58:61]
	v_mfma_f32_16x16x32_bf16 v[54:57], v[142:145], v[174:177], v[54:57]
	v_mfma_f32_16x16x32_bf16 v[54:57], v[146:149], v[202:205], v[54:57]
	v_mfma_f32_16x16x32_bf16 v[50:53], v[134:137], v[206:209], v[50:53]
	v_mfma_f32_16x16x32_bf16 v[50:53], v[138:141], v[210:213], v[50:53]
	v_mfma_f32_16x16x32_bf16 v[46:49], v[142:145], v[206:209], v[46:49]
	v_mfma_f32_16x16x32_bf16 v[46:49], v[146:149], v[210:213], v[46:49]
	v_mfma_f32_16x16x32_bf16 v[42:45], v[134:137], v[214:217], v[42:45]
	v_mfma_f32_16x16x32_bf16 v[42:45], v[138:141], v[218:221], v[42:45]
	v_mfma_f32_16x16x32_bf16 v[38:41], v[142:145], v[214:217], v[38:41]
	v_mfma_f32_16x16x32_bf16 v[38:41], v[146:149], v[218:221], v[38:41]
	v_mfma_f32_16x16x32_bf16 v[34:37], v[150:153], v[166:169], v[34:37]
	v_mfma_f32_16x16x32_bf16 v[34:37], v[154:157], v[170:173], v[34:37]
	v_mfma_f32_16x16x32_bf16 v[30:33], v[158:161], v[166:169], v[30:33]
	v_mfma_f32_16x16x32_bf16 v[30:33], v[162:165], v[170:173], v[30:33]
	v_mfma_f32_16x16x32_bf16 v[26:29], v[150:153], v[174:177], v[26:29]
	v_mfma_f32_16x16x32_bf16 v[26:29], v[154:157], v[202:205], v[26:29]
	v_mfma_f32_16x16x32_bf16 v[22:25], v[158:161], v[174:177], v[22:25]
	v_mfma_f32_16x16x32_bf16 v[22:25], v[162:165], v[202:205], v[22:25]
	v_mfma_f32_16x16x32_bf16 v[18:21], v[150:153], v[206:209], v[18:21]
	v_mfma_f32_16x16x32_bf16 v[18:21], v[154:157], v[210:213], v[18:21]
	v_mfma_f32_16x16x32_bf16 v[14:17], v[158:161], v[206:209], v[14:17]
	v_mfma_f32_16x16x32_bf16 v[14:17], v[162:165], v[210:213], v[14:17]
	v_mfma_f32_16x16x32_bf16 v[10:13], v[150:153], v[214:217], v[10:13]
	v_mfma_f32_16x16x32_bf16 v[10:13], v[154:157], v[218:221], v[10:13]
	v_mfma_f32_16x16x32_bf16 v[6:9], v[158:161], v[214:217], v[6:9]
	v_mfma_f32_16x16x32_bf16 v[6:9], v[162:165], v[218:221], v[6:9]
	s_barrier
	s_add_i32 s84, 0, 0x18000
	s_add_i32 s85, 0, 0x1c000
	ds_read_b128 v[134:137], v246
	ds_read_b128 v[138:141], v246 offset:1024
	ds_read_b128 v[142:145], v246 offset:2048
	ds_read_b128 v[146:149], v246 offset:3072
	ds_read_b128 v[150:153], v247
	ds_read_b128 v[154:157], v247 offset:1024
	ds_read_b128 v[158:161], v247 offset:2048
	ds_read_b128 v[162:165], v247 offset:3072
	s_add_u32 s100, s58, 0x80
	s_addc_u32 s101, s59, 0
	s_add_u32 s58, s58, 0x100000
	s_addc_u32 s59, s59, 0
	s_mov_b32 m0, s67
	ds_read_b128 v[166:169], v230 offset:32768
	ds_read_b128 v[170:173], v230 offset:33792
	ds_read_b128 v[174:177], v230 offset:34816
	ds_read_b128 v[202:205], v230 offset:35840
	ds_read_b128 v[206:209], v230 offset:36864
	ds_read_b128 v[210:213], v230 offset:37888
	ds_read_b128 v[214:217], v230 offset:38912
	ds_read_b128 v[218:221], v230 offset:39936
	global_load_lds_dwordx4 v178, s[58:59]
	s_mov_b32 m0, s68
	s_nop 0
	global_load_lds_dwordx4 v182, s[58:59]
	s_waitcnt vmcnt(8)
	s_waitcnt lgkmcnt(0)
	s_barrier
	v_mfma_f32_16x16x32_bf16 v[2:5], v[134:137], v[166:169], v[2:5]
	v_mfma_f32_16x16x32_bf16 v[2:5], v[138:141], v[170:173], v[2:5]
	v_mfma_f32_16x16x32_bf16 v[126:129], v[142:145], v[166:169], v[126:129]
	v_mfma_f32_16x16x32_bf16 v[126:129], v[146:149], v[170:173], v[126:129]
	v_mfma_f32_16x16x32_bf16 v[122:125], v[134:137], v[174:177], v[122:125]
	v_mfma_f32_16x16x32_bf16 v[122:125], v[138:141], v[202:205], v[122:125]
	v_mfma_f32_16x16x32_bf16 v[118:121], v[142:145], v[174:177], v[118:121]
	v_mfma_f32_16x16x32_bf16 v[118:121], v[146:149], v[202:205], v[118:121]
	v_mfma_f32_16x16x32_bf16 v[114:117], v[134:137], v[206:209], v[114:117]
	v_mfma_f32_16x16x32_bf16 v[114:117], v[138:141], v[210:213], v[114:117]
	v_mfma_f32_16x16x32_bf16 v[110:113], v[142:145], v[206:209], v[110:113]
	v_mfma_f32_16x16x32_bf16 v[110:113], v[146:149], v[210:213], v[110:113]
	v_mfma_f32_16x16x32_bf16 v[106:109], v[134:137], v[214:217], v[106:109]
	v_mfma_f32_16x16x32_bf16 v[106:109], v[138:141], v[218:221], v[106:109]
	v_mfma_f32_16x16x32_bf16 v[102:105], v[142:145], v[214:217], v[102:105]
	v_mfma_f32_16x16x32_bf16 v[102:105], v[146:149], v[218:221], v[102:105]
	v_mfma_f32_16x16x32_bf16 v[98:101], v[150:153], v[166:169], v[98:101]
	v_mfma_f32_16x16x32_bf16 v[98:101], v[154:157], v[170:173], v[98:101]
	v_mfma_f32_16x16x32_bf16 v[94:97], v[158:161], v[166:169], v[94:97]
	v_mfma_f32_16x16x32_bf16 v[94:97], v[162:165], v[170:173], v[94:97]
	v_mfma_f32_16x16x32_bf16 v[90:93], v[150:153], v[174:177], v[90:93]
	v_mfma_f32_16x16x32_bf16 v[90:93], v[154:157], v[202:205], v[90:93]
	v_mfma_f32_16x16x32_bf16 v[86:89], v[158:161], v[174:177], v[86:89]
	v_mfma_f32_16x16x32_bf16 v[86:89], v[162:165], v[202:205], v[86:89]
	v_mfma_f32_16x16x32_bf16 v[82:85], v[150:153], v[206:209], v[82:85]
	v_mfma_f32_16x16x32_bf16 v[82:85], v[154:157], v[210:213], v[82:85]
	v_mfma_f32_16x16x32_bf16 v[78:81], v[158:161], v[206:209], v[78:81]
	v_mfma_f32_16x16x32_bf16 v[78:81], v[162:165], v[210:213], v[78:81]
	v_mfma_f32_16x16x32_bf16 v[74:77], v[150:153], v[214:217], v[74:77]
	v_mfma_f32_16x16x32_bf16 v[74:77], v[154:157], v[218:221], v[74:77]
	v_mfma_f32_16x16x32_bf16 v[70:73], v[158:161], v[214:217], v[70:73]
	v_mfma_f32_16x16x32_bf16 v[70:73], v[162:165], v[218:221], v[70:73]
	s_barrier
	s_add_i32 s58, s84, s63
	s_add_u32 s98, s56, 0x80
	s_addc_u32 s99, s57, 0
	s_mov_b32 m0, s58
	ds_read_b128 v[166:169], v230 offset:49152
	ds_read_b128 v[170:173], v230 offset:50176
	ds_read_b128 v[174:177], v230 offset:51200
	ds_read_b128 v[202:205], v230 offset:52224
	ds_read_b128 v[206:209], v230 offset:53248
	ds_read_b128 v[210:213], v230 offset:54272
	ds_read_b128 v[214:217], v230 offset:55296
	ds_read_b128 v[218:221], v230 offset:56320
	global_load_lds_dwordx4 v180, s[98:99]
	s_add_i32 m0, s58, 0x2000
	s_add_u32 s56, s56, 0x100080
	s_addc_u32 s57, s57, 0
	s_add_i32 s58, s85, s63
	global_load_lds_dwordx4 v184, s[98:99]
	s_mov_b32 m0, s58
	s_nop 0
	global_load_lds_dwordx4 v180, s[56:57]
	s_add_i32 m0, s58, 0x2000
	s_nop 0
	global_load_lds_dwordx4 v184, s[56:57]
	s_mov_b32 m0, s74
	s_nop 0
	global_load_lds_dwordx4 v178, s[100:101]
	s_mov_b32 m0, s75
	s_nop 0
	global_load_lds_dwordx4 v182, s[100:101]
	s_waitcnt vmcnt(8)
	s_waitcnt lgkmcnt(0)
	s_barrier
	v_mfma_f32_16x16x32_bf16 v[66:69], v[134:137], v[166:169], v[66:69]
	v_mfma_f32_16x16x32_bf16 v[66:69], v[138:141], v[170:173], v[66:69]
	v_mfma_f32_16x16x32_bf16 v[62:65], v[142:145], v[166:169], v[62:65]
	v_mfma_f32_16x16x32_bf16 v[62:65], v[146:149], v[170:173], v[62:65]
	v_mfma_f32_16x16x32_bf16 v[58:61], v[134:137], v[174:177], v[58:61]
	v_mfma_f32_16x16x32_bf16 v[58:61], v[138:141], v[202:205], v[58:61]
	v_mfma_f32_16x16x32_bf16 v[54:57], v[142:145], v[174:177], v[54:57]
	v_mfma_f32_16x16x32_bf16 v[54:57], v[146:149], v[202:205], v[54:57]
	v_mfma_f32_16x16x32_bf16 v[50:53], v[134:137], v[206:209], v[50:53]
	v_mfma_f32_16x16x32_bf16 v[50:53], v[138:141], v[210:213], v[50:53]
	v_mfma_f32_16x16x32_bf16 v[46:49], v[142:145], v[206:209], v[46:49]
	v_mfma_f32_16x16x32_bf16 v[46:49], v[146:149], v[210:213], v[46:49]
	v_mfma_f32_16x16x32_bf16 v[42:45], v[134:137], v[214:217], v[42:45]
	v_mfma_f32_16x16x32_bf16 v[42:45], v[138:141], v[218:221], v[42:45]
	v_mfma_f32_16x16x32_bf16 v[38:41], v[142:145], v[214:217], v[38:41]
	v_mfma_f32_16x16x32_bf16 v[38:41], v[146:149], v[218:221], v[38:41]
	v_mfma_f32_16x16x32_bf16 v[34:37], v[150:153], v[166:169], v[34:37]
	v_mfma_f32_16x16x32_bf16 v[34:37], v[154:157], v[170:173], v[34:37]
	v_mfma_f32_16x16x32_bf16 v[30:33], v[158:161], v[166:169], v[30:33]
	v_mfma_f32_16x16x32_bf16 v[30:33], v[162:165], v[170:173], v[30:33]
	v_mfma_f32_16x16x32_bf16 v[26:29], v[150:153], v[174:177], v[26:29]
	v_mfma_f32_16x16x32_bf16 v[26:29], v[154:157], v[202:205], v[26:29]
	v_mfma_f32_16x16x32_bf16 v[22:25], v[158:161], v[174:177], v[22:25]
	v_mfma_f32_16x16x32_bf16 v[22:25], v[162:165], v[202:205], v[22:25]
	v_mfma_f32_16x16x32_bf16 v[18:21], v[150:153], v[206:209], v[18:21]
	v_mfma_f32_16x16x32_bf16 v[18:21], v[154:157], v[210:213], v[18:21]
	v_mfma_f32_16x16x32_bf16 v[14:17], v[158:161], v[206:209], v[14:17]
	v_mfma_f32_16x16x32_bf16 v[14:17], v[162:165], v[210:213], v[14:17]
	v_mfma_f32_16x16x32_bf16 v[10:13], v[150:153], v[214:217], v[10:13]
	v_mfma_f32_16x16x32_bf16 v[10:13], v[154:157], v[218:221], v[10:13]
	v_mfma_f32_16x16x32_bf16 v[6:9], v[158:161], v[214:217], v[6:9]
	v_mfma_f32_16x16x32_bf16 v[6:9], v[162:165], v[218:221], v[6:9]
	s_barrier
	s_add_i32 s83, s83, 2
	s_add_u32 s10, s10, 0x100
	s_addc_u32 s11, s11, 0
	s_cmp_gt_u32 s83, 61
	s_cbranch_scc0 .LBB0_1153
	s_setprio 0
	s_and_b64 vcc, exec, s[36:37]
	s_cbranch_vccz .LBB0_1156
	s_barrier

.LBB0_1324:
	s_add_u32 s24, s24, 0x2b0080
	s_addc_u32 s25, s25, 0
	s_add_u32 s47, s26, 0x100
	v_mov_b32_e32 v2, 0
	s_addc_u32 s48, s27, 0
	s_mov_b32 s49, -2
	v_mov_b64_e32 v[2:3], 0
	v_mov_b64_e32 v[4:5], 0
	v_mov_b64_e32 v[6:7], 0
	v_mov_b64_e32 v[8:9], 0
	v_mov_b64_e32 v[10:11], 0
	v_mov_b64_e32 v[12:13], 0
	v_mov_b64_e32 v[14:15], 0
	v_mov_b64_e32 v[16:17], 0
	v_mov_b64_e32 v[18:19], 0
	v_mov_b64_e32 v[20:21], 0
	v_mov_b64_e32 v[22:23], 0
	v_mov_b64_e32 v[24:25], 0
	v_mov_b64_e32 v[26:27], 0
	v_mov_b64_e32 v[28:29], 0
	v_mov_b64_e32 v[30:31], 0
	v_mov_b64_e32 v[32:33], 0
	v_mov_b64_e32 v[34:35], 0
	v_mov_b64_e32 v[36:37], 0
	v_mov_b64_e32 v[38:39], 0
	v_mov_b64_e32 v[40:41], 0
	v_mov_b64_e32 v[42:43], 0
	v_mov_b64_e32 v[44:45], 0
	v_mov_b64_e32 v[46:47], 0
	v_mov_b64_e32 v[48:49], 0
	v_mov_b64_e32 v[50:51], 0
	v_mov_b64_e32 v[52:53], 0
	v_mov_b64_e32 v[54:55], 0
	v_mov_b64_e32 v[56:57], 0
	v_mov_b64_e32 v[58:59], 0
	v_mov_b64_e32 v[60:61], 0
	v_mov_b64_e32 v[62:63], 0
	v_mov_b64_e32 v[64:65], 0
	v_mov_b64_e32 v[66:67], 0
	v_mov_b64_e32 v[68:69], 0
	v_mov_b64_e32 v[70:71], 0
	v_mov_b64_e32 v[72:73], 0
	v_mov_b64_e32 v[82:83], 0
	v_mov_b64_e32 v[84:85], 0
	v_mov_b64_e32 v[86:87], 0
	v_mov_b64_e32 v[88:89], 0
	s_waitcnt vmcnt(0)
	v_mov_b64_e32 v[74:75], 0
	v_mov_b64_e32 v[76:77], 0
	v_mov_b64_e32 v[78:79], 0
	v_mov_b64_e32 v[80:81], 0
	v_mov_b64_e32 v[90:91], 0
	v_mov_b64_e32 v[92:93], 0
	v_mov_b64_e32 v[94:95], 0
	v_mov_b64_e32 v[96:97], 0
	v_mov_b64_e32 v[98:99], 0
	v_mov_b64_e32 v[100:101], 0
	v_mov_b64_e32 v[102:103], 0
	v_mov_b64_e32 v[104:105], 0
	v_mov_b64_e32 v[106:107], 0
	v_mov_b64_e32 v[108:109], 0
	v_mov_b64_e32 v[110:111], 0
	v_mov_b64_e32 v[112:113], 0
	v_mov_b64_e32 v[114:115], 0
	v_mov_b64_e32 v[116:117], 0
	v_mov_b64_e32 v[118:119], 0
	v_mov_b64_e32 v[120:121], 0
	v_mov_b64_e32 v[122:123], 0
	v_mov_b64_e32 v[124:125], 0
	v_mov_b64_e32 v[126:127], 0
	v_mov_b64_e32 v[128:129], 0
	v_add_u32_e32 v246, 0x18000, v174
	v_add_u32_e32 v247, 0x1c000, v174
	v_cmp_gt_u32_e32 vcc, 0x100, v0
	s_cbranch_vccnz .Lgprio_1325
	s_setprio 1
.Lgprio_1325:
.LBB0_1325:
	ds_read_b128 v[130:133], v176
	ds_read_b128 v[134:137], v176 offset:1024
	ds_read_b128 v[138:141], v176 offset:2048
	ds_read_b128 v[142:145], v176 offset:3072
	ds_read_b128 v[146:149], v177
	ds_read_b128 v[166:169], v177 offset:1024
	ds_read_b128 v[170:173], v177 offset:2048
	ds_read_b128 v[180:183], v177 offset:3072
	s_add_u32 s26, s24, 0xffd50080
	s_addc_u32 s27, s25, -1
	s_cmpk_eq_i32 s49, 0xa8
	s_cselect_b32 s29, s5, s27
	s_cselect_b32 s28, s4, s26
	s_cselect_b32 s27, s23, s48
	s_cselect_b32 s26, s22, s47
	s_add_i32 m0, s33, 0xc000
	ds_read_b128 v[184:187], v178
	ds_read_b128 v[188:191], v178 offset:1024
	ds_read_b128 v[192:195], v178 offset:2048
	ds_read_b128 v[196:199], v178 offset:3072
	ds_read_b128 v[200:203], v178 offset:4096
	ds_read_b128 v[204:207], v178 offset:5120
	ds_read_b128 v[208:211], v178 offset:6144
	ds_read_b128 v[212:215], v178 offset:7168
	global_load_lds_dwordx4 v158, s[24:25]
	s_add_i32 m0, s33, 0xe000
	s_nop 0
	global_load_lds_dwordx4 v160, s[24:25]
	s_waitcnt vmcnt(8)
	s_waitcnt lgkmcnt(0)
	s_barrier
	v_mfma_f32_16x16x32_bf16 v[126:129], v[130:133], v[184:187], v[126:129]
	v_mfma_f32_16x16x32_bf16 v[126:129], v[134:137], v[188:191], v[126:129]
	v_mfma_f32_16x16x32_bf16 v[122:125], v[138:141], v[184:187], v[122:125]
	v_mfma_f32_16x16x32_bf16 v[122:125], v[142:145], v[188:191], v[122:125]
	v_mfma_f32_16x16x32_bf16 v[110:113], v[130:133], v[192:195], v[110:113]
	v_mfma_f32_16x16x32_bf16 v[110:113], v[134:137], v[196:199], v[110:113]
	v_mfma_f32_16x16x32_bf16 v[106:109], v[138:141], v[192:195], v[106:109]
	v_mfma_f32_16x16x32_bf16 v[106:109], v[142:145], v[196:199], v[106:109]
	v_mfma_f32_16x16x32_bf16 v[94:97], v[130:133], v[200:203], v[94:97]
	v_mfma_f32_16x16x32_bf16 v[94:97], v[134:137], v[204:207], v[94:97]
	v_mfma_f32_16x16x32_bf16 v[90:93], v[138:141], v[200:203], v[90:93]
	v_mfma_f32_16x16x32_bf16 v[90:93], v[142:145], v[204:207], v[90:93]
	v_mfma_f32_16x16x32_bf16 v[78:81], v[130:133], v[208:211], v[78:81]
	v_mfma_f32_16x16x32_bf16 v[78:81], v[134:137], v[212:215], v[78:81]
	v_mfma_f32_16x16x32_bf16 v[74:77], v[138:141], v[208:211], v[74:77]
	v_mfma_f32_16x16x32_bf16 v[74:77], v[142:145], v[212:215], v[74:77]
	v_mfma_f32_16x16x32_bf16 v[118:121], v[146:149], v[184:187], v[118:121]
	v_mfma_f32_16x16x32_bf16 v[118:121], v[166:169], v[188:191], v[118:121]
	v_mfma_f32_16x16x32_bf16 v[114:117], v[170:173], v[184:187], v[114:117]
	v_mfma_f32_16x16x32_bf16 v[114:117], v[180:183], v[188:191], v[114:117]
	v_mfma_f32_16x16x32_bf16 v[102:105], v[146:149], v[192:195], v[102:105]
	v_mfma_f32_16x16x32_bf16 v[102:105], v[166:169], v[196:199], v[102:105]
	v_mfma_f32_16x16x32_bf16 v[98:101], v[170:173], v[192:195], v[98:101]
	v_mfma_f32_16x16x32_bf16 v[98:101], v[180:183], v[196:199], v[98:101]
	v_mfma_f32_16x16x32_bf16 v[86:89], v[146:149], v[200:203], v[86:89]
	v_mfma_f32_16x16x32_bf16 v[86:89], v[166:169], v[204:207], v[86:89]
	v_mfma_f32_16x16x32_bf16 v[82:85], v[170:173], v[200:203], v[82:85]
	v_mfma_f32_16x16x32_bf16 v[82:85], v[180:183], v[204:207], v[82:85]
	v_mfma_f32_16x16x32_bf16 v[70:73], v[146:149], v[208:211], v[70:73]
	v_mfma_f32_16x16x32_bf16 v[70:73], v[166:169], v[212:215], v[70:73]
	v_mfma_f32_16x16x32_bf16 v[66:69], v[170:173], v[208:211], v[66:69]
	v_mfma_f32_16x16x32_bf16 v[66:69], v[180:183], v[212:215], v[66:69]
	s_barrier
	s_add_i32 s50, s41, s31
	s_mov_b32 m0, s50
	ds_read_b128 v[184:187], v178 offset:16384
	ds_read_b128 v[188:191], v178 offset:17408
	ds_read_b128 v[192:195], v178 offset:18432
	ds_read_b128 v[196:199], v178 offset:19456
	ds_read_b128 v[200:203], v178 offset:20480
	ds_read_b128 v[204:207], v178 offset:21504
	ds_read_b128 v[208:211], v178 offset:22528
	ds_read_b128 v[212:215], v178 offset:23552
	global_load_lds_dwordx4 v152, s[26:27]
	s_add_i32 m0, s50, 0x2000
	s_add_u32 s50, s26, 0x2b0000
	s_addc_u32 s51, s27, 0
	s_add_i32 s52, s42, s31
	global_load_lds_dwordx4 v156, s[26:27]
	s_mov_b32 m0, s52
	global_load_lds_dwordx4 v152, s[50:51]
	s_add_i32 m0, s52, 0x2000
	s_nop 0
	global_load_lds_dwordx4 v156, s[50:51]
	s_mov_b32 m0, s33
	s_nop 0
	global_load_lds_dwordx4 v150, s[28:29]
	s_mov_b32 m0, s34
	s_nop 0
	global_load_lds_dwordx4 v154, s[28:29]
	s_waitcnt vmcnt(8)
	s_waitcnt lgkmcnt(0)
	s_barrier
	v_mfma_f32_16x16x32_bf16 v[62:65], v[130:133], v[184:187], v[62:65]
	v_mfma_f32_16x16x32_bf16 v[62:65], v[134:137], v[188:191], v[62:65]
	v_mfma_f32_16x16x32_bf16 v[58:61], v[138:141], v[184:187], v[58:61]
	v_mfma_f32_16x16x32_bf16 v[58:61], v[142:145], v[188:191], v[58:61]
	v_mfma_f32_16x16x32_bf16 v[46:49], v[130:133], v[192:195], v[46:49]
	v_mfma_f32_16x16x32_bf16 v[46:49], v[134:137], v[196:199], v[46:49]
	v_mfma_f32_16x16x32_bf16 v[42:45], v[138:141], v[192:195], v[42:45]
	v_mfma_f32_16x16x32_bf16 v[42:45], v[142:145], v[196:199], v[42:45]
	v_mfma_f32_16x16x32_bf16 v[30:33], v[130:133], v[200:203], v[30:33]
	v_mfma_f32_16x16x32_bf16 v[30:33], v[134:137], v[204:207], v[30:33]
	v_mfma_f32_16x16x32_bf16 v[26:29], v[138:141], v[200:203], v[26:29]
	v_mfma_f32_16x16x32_bf16 v[26:29], v[142:145], v[204:207], v[26:29]
	v_mfma_f32_16x16x32_bf16 v[14:17], v[130:133], v[208:211], v[14:17]
	v_mfma_f32_16x16x32_bf16 v[14:17], v[134:137], v[212:215], v[14:17]
	v_mfma_f32_16x16x32_bf16 v[10:13], v[138:141], v[208:211], v[10:13]
	v_mfma_f32_16x16x32_bf16 v[10:13], v[142:145], v[212:215], v[10:13]
	v_mfma_f32_16x16x32_bf16 v[54:57], v[146:149], v[184:187], v[54:57]
	v_mfma_f32_16x16x32_bf16 v[54:57], v[166:169], v[188:191], v[54:57]
	v_mfma_f32_16x16x32_bf16 v[50:53], v[170:173], v[184:187], v[50:53]
	v_mfma_f32_16x16x32_bf16 v[50:53], v[180:183], v[188:191], v[50:53]
	v_mfma_f32_16x16x32_bf16 v[38:41], v[146:149], v[192:195], v[38:41]
	v_mfma_f32_16x16x32_bf16 v[38:41], v[166:169], v[196:199], v[38:41]
	v_mfma_f32_16x16x32_bf16 v[34:37], v[170:173], v[192:195], v[34:37]
	v_mfma_f32_16x16x32_bf16 v[34:37], v[180:183], v[196:199], v[34:37]
	v_mfma_f32_16x16x32_bf16 v[22:25], v[146:149], v[200:203], v[22:25]
	v_mfma_f32_16x16x32_bf16 v[22:25], v[166:169], v[204:207], v[22:25]
	v_mfma_f32_16x16x32_bf16 v[18:21], v[170:173], v[200:203], v[18:21]
	v_mfma_f32_16x16x32_bf16 v[18:21], v[180:183], v[204:207], v[18:21]
	v_mfma_f32_16x16x32_bf16 v[6:9], v[146:149], v[208:211], v[6:9]
	v_mfma_f32_16x16x32_bf16 v[6:9], v[166:169], v[212:215], v[6:9]
	v_mfma_f32_16x16x32_bf16 v[2:5], v[170:173], v[208:211], v[2:5]
	v_mfma_f32_16x16x32_bf16 v[2:5], v[180:183], v[212:215], v[2:5]
	s_barrier
	s_add_i32 s50, 0, 0x18000
	s_add_i32 s51, 0, 0x1c000
	ds_read_b128 v[130:133], v246
	ds_read_b128 v[134:137], v246 offset:1024
	ds_read_b128 v[138:141], v246 offset:2048
	ds_read_b128 v[142:145], v246 offset:3072
	ds_read_b128 v[146:149], v247
	ds_read_b128 v[166:169], v247 offset:1024
	ds_read_b128 v[170:173], v247 offset:2048
	ds_read_b128 v[180:183], v247 offset:3072
	s_add_u32 s98, s28, 0x80
	s_addc_u32 s99, s29, 0
	s_add_u32 s28, s28, 0x2b0000
	s_addc_u32 s29, s29, 0
	s_mov_b32 m0, s35
	ds_read_b128 v[184:187], v178 offset:32768
	ds_read_b128 v[188:191], v178 offset:33792
	ds_read_b128 v[192:195], v178 offset:34816
	ds_read_b128 v[196:199], v178 offset:35840
	ds_read_b128 v[200:203], v178 offset:36864
	ds_read_b128 v[204:207], v178 offset:37888
	ds_read_b128 v[208:211], v178 offset:38912
	ds_read_b128 v[212:215], v178 offset:39936
	global_load_lds_dwordx4 v150, s[28:29]
	s_mov_b32 m0, s36
	s_nop 0
	global_load_lds_dwordx4 v154, s[28:29]
	s_waitcnt vmcnt(8)
	s_waitcnt lgkmcnt(0)
	s_barrier
	v_mfma_f32_16x16x32_bf16 v[126:129], v[130:133], v[184:187], v[126:129]
	v_mfma_f32_16x16x32_bf16 v[126:129], v[134:137], v[188:191], v[126:129]
	v_mfma_f32_16x16x32_bf16 v[122:125], v[138:141], v[184:187], v[122:125]
	v_mfma_f32_16x16x32_bf16 v[122:125], v[142:145], v[188:191], v[122:125]
	v_mfma_f32_16x16x32_bf16 v[110:113], v[130:133], v[192:195], v[110:113]
	v_mfma_f32_16x16x32_bf16 v[110:113], v[134:137], v[196:199], v[110:113]
	v_mfma_f32_16x16x32_bf16 v[106:109], v[138:141], v[192:195], v[106:109]
	v_mfma_f32_16x16x32_bf16 v[106:109], v[142:145], v[196:199], v[106:109]
	v_mfma_f32_16x16x32_bf16 v[94:97], v[130:133], v[200:203], v[94:97]
	v_mfma_f32_16x16x32_bf16 v[94:97], v[134:137], v[204:207], v[94:97]
	v_mfma_f32_16x16x32_bf16 v[90:93], v[138:141], v[200:203], v[90:93]
	v_mfma_f32_16x16x32_bf16 v[90:93], v[142:145], v[204:207], v[90:93]
	v_mfma_f32_16x16x32_bf16 v[78:81], v[130:133], v[208:211], v[78:81]
	v_mfma_f32_16x16x32_bf16 v[78:81], v[134:137], v[212:215], v[78:81]
	v_mfma_f32_16x16x32_bf16 v[74:77], v[138:141], v[208:211], v[74:77]
	v_mfma_f32_16x16x32_bf16 v[74:77], v[142:145], v[212:215], v[74:77]
	v_mfma_f32_16x16x32_bf16 v[118:121], v[146:149], v[184:187], v[118:121]
	v_mfma_f32_16x16x32_bf16 v[118:121], v[166:169], v[188:191], v[118:121]
	v_mfma_f32_16x16x32_bf16 v[114:117], v[170:173], v[184:187], v[114:117]
	v_mfma_f32_16x16x32_bf16 v[114:117], v[180:183], v[188:191], v[114:117]
	v_mfma_f32_16x16x32_bf16 v[102:105], v[146:149], v[192:195], v[102:105]
	v_mfma_f32_16x16x32_bf16 v[102:105], v[166:169], v[196:199], v[102:105]
	v_mfma_f32_16x16x32_bf16 v[98:101], v[170:173], v[192:195], v[98:101]
	v_mfma_f32_16x16x32_bf16 v[98:101], v[180:183], v[196:199], v[98:101]
	v_mfma_f32_16x16x32_bf16 v[86:89], v[146:149], v[200:203], v[86:89]
	v_mfma_f32_16x16x32_bf16 v[86:89], v[166:169], v[204:207], v[86:89]
	v_mfma_f32_16x16x32_bf16 v[82:85], v[170:173], v[200:203], v[82:85]
	v_mfma_f32_16x16x32_bf16 v[82:85], v[180:183], v[204:207], v[82:85]
	v_mfma_f32_16x16x32_bf16 v[70:73], v[146:149], v[208:211], v[70:73]
	v_mfma_f32_16x16x32_bf16 v[70:73], v[166:169], v[212:215], v[70:73]
	v_mfma_f32_16x16x32_bf16 v[66:69], v[170:173], v[208:211], v[66:69]
	v_mfma_f32_16x16x32_bf16 v[66:69], v[180:183], v[212:215], v[66:69]
	s_barrier
	s_add_i32 s28, s50, s31
	s_mov_b32 m0, s28
	ds_read_b128 v[184:187], v178 offset:49152
	ds_read_b128 v[188:191], v178 offset:50176
	ds_read_b128 v[192:195], v178 offset:51200
	ds_read_b128 v[196:199], v178 offset:52224
	ds_read_b128 v[200:203], v178 offset:53248
	ds_read_b128 v[204:207], v178 offset:54272
	ds_read_b128 v[208:211], v178 offset:55296
	ds_read_b128 v[212:215], v178 offset:56320
	s_add_u32 s26, s26, 0x80
	s_addc_u32 s27, s27, 0
	global_load_lds_dwordx4 v152, s[26:27]
	s_add_i32 m0, s28, 0x2000
	s_add_i32 s28, s51, s31
	global_load_lds_dwordx4 v156, s[26:27]
	s_add_u32 s26, s26, 0x2b0000
	s_addc_u32 s27, s27, 0
	s_mov_b32 m0, s28
	s_nop 0
	global_load_lds_dwordx4 v152, s[26:27]
	s_add_i32 m0, s28, 0x2000
	s_nop 0
	global_load_lds_dwordx4 v156, s[26:27]
	s_mov_b32 m0, s38
	s_nop 0
	global_load_lds_dwordx4 v150, s[98:99]
	s_mov_b32 m0, s39
	s_nop 0
	global_load_lds_dwordx4 v154, s[98:99]
	s_waitcnt vmcnt(8)
	s_waitcnt lgkmcnt(0)
	s_barrier
	v_mfma_f32_16x16x32_bf16 v[62:65], v[130:133], v[184:187], v[62:65]
	v_mfma_f32_16x16x32_bf16 v[62:65], v[134:137], v[188:191], v[62:65]
	v_mfma_f32_16x16x32_bf16 v[58:61], v[138:141], v[184:187], v[58:61]
	v_mfma_f32_16x16x32_bf16 v[58:61], v[142:145], v[188:191], v[58:61]
	v_mfma_f32_16x16x32_bf16 v[46:49], v[130:133], v[192:195], v[46:49]
	v_mfma_f32_16x16x32_bf16 v[46:49], v[134:137], v[196:199], v[46:49]
	v_mfma_f32_16x16x32_bf16 v[42:45], v[138:141], v[192:195], v[42:45]
	v_mfma_f32_16x16x32_bf16 v[42:45], v[142:145], v[196:199], v[42:45]
	v_mfma_f32_16x16x32_bf16 v[30:33], v[130:133], v[200:203], v[30:33]
	v_mfma_f32_16x16x32_bf16 v[30:33], v[134:137], v[204:207], v[30:33]
	v_mfma_f32_16x16x32_bf16 v[26:29], v[138:141], v[200:203], v[26:29]
	v_mfma_f32_16x16x32_bf16 v[26:29], v[142:145], v[204:207], v[26:29]
	v_mfma_f32_16x16x32_bf16 v[14:17], v[130:133], v[208:211], v[14:17]
	v_mfma_f32_16x16x32_bf16 v[14:17], v[134:137], v[212:215], v[14:17]
	v_mfma_f32_16x16x32_bf16 v[10:13], v[138:141], v[208:211], v[10:13]
	v_mfma_f32_16x16x32_bf16 v[10:13], v[142:145], v[212:215], v[10:13]
	v_mfma_f32_16x16x32_bf16 v[54:57], v[146:149], v[184:187], v[54:57]
	v_mfma_f32_16x16x32_bf16 v[54:57], v[166:169], v[188:191], v[54:57]
	v_mfma_f32_16x16x32_bf16 v[50:53], v[170:173], v[184:187], v[50:53]
	v_mfma_f32_16x16x32_bf16 v[50:53], v[180:183], v[188:191], v[50:53]
	v_mfma_f32_16x16x32_bf16 v[38:41], v[146:149], v[192:195], v[38:41]
	v_mfma_f32_16x16x32_bf16 v[38:41], v[166:169], v[196:199], v[38:41]
	v_mfma_f32_16x16x32_bf16 v[34:37], v[170:173], v[192:195], v[34:37]
	v_mfma_f32_16x16x32_bf16 v[34:37], v[180:183], v[196:199], v[34:37]
	v_mfma_f32_16x16x32_bf16 v[22:25], v[146:149], v[200:203], v[22:25]
	v_mfma_f32_16x16x32_bf16 v[22:25], v[166:169], v[204:207], v[22:25]
	v_mfma_f32_16x16x32_bf16 v[18:21], v[170:173], v[200:203], v[18:21]
	v_mfma_f32_16x16x32_bf16 v[18:21], v[180:183], v[204:207], v[18:21]
	v_mfma_f32_16x16x32_bf16 v[6:9], v[146:149], v[208:211], v[6:9]
	v_mfma_f32_16x16x32_bf16 v[6:9], v[166:169], v[212:215], v[6:9]
	v_mfma_f32_16x16x32_bf16 v[2:5], v[170:173], v[208:211], v[2:5]
	v_mfma_f32_16x16x32_bf16 v[2:5], v[180:183], v[212:215], v[2:5]
	s_barrier
	s_add_i32 s49, s49, 2
	s_add_u32 s24, s24, 0x100
	s_addc_u32 s25, s25, 0
	s_add_u32 s47, s47, 0x100
	s_addc_u32 s48, s48, 0
	s_cmpk_gt_u32 s49, 0xa9
	s_cbranch_scc0 .LBB0_1325
	s_setprio 0
	s_and_b64 vcc, exec, s[10:11]
	s_cbranch_vccz .LBB0_1328
	s_barrier
